# v56: v55 + s_setprio 3 inside the passB serial sections (gate scan, stabiliser scan, n.q dot; waves 0-3), reset to 0 at the join
# speedup vs baseline: 1.0008x; 1.0008x over previous
; #define LAS __attribute__((address_space(3)))
; __device__ void passB_unit(const Params& p, LAS unsigned char* lds, int u, bool do_store = true) {
;     ...
;     float sc_b = 0.f, sc_li = 0.f; int sc_t = 0;
;     if (tid < 256) { const int d = tid >> 7, i = tid & 127; sc_t = d ? 127 - i : i;
;         sc_li = GL[(size_t)(d * 8 + h) * 2048 + sc_t]; float inc = GL[(size_t)(d * 8 + 4 + h) * 2048 + sc_t];
; #pragma unroll
;         for (int off = 1; off < 64; off <<= 1) { const float n = __shfl_up(inc, off); inc += (lane >= off) ? n : 0.f; }
;         sc_b = inc; if (lane == 63) wtot[wid] = inc; }
;     { const int d = tid >> 8, k = tid & 255; nvec[tid] = ((const float*)(p.ws + OFF_NST))[(size_t)((sid0 + d) * 16 + c) * 256 + k]; }
; #pragma unroll
;     for (int i = 0; i < 8; ++i) { const int id = tid + 512 * i; const int w = id >> 9, m = (id >> 7) & 3, bj = (id >> 6) & 1, ln = id & 63;
;         *(LAS u32x4*)(Qs + ((w >> 2) * 64 + m * 16 + (ln & 15)) * 264 + bj * 128 + (w & 3) * 32 + (ln >> 4) * 8) = __builtin_nontemporal_load((const u32x4*)(Qg + (size_t)((w * 16 + m * 2 + bj) * 64 + ln) * 8)); }
.LBB0_533:
	s_lshl_b32 s0, s2, 1
	v_mov_b32_e32 v196, v224
	s_and_b32 s52, s0, 14
	s_movk_i32 s0, 0x100
	s_lshl_b32 s10, s52, 7
	v_ashrrev_i32_e32 v68, 6, v196
	v_and_b32_e32 v197, 63, v196
	v_cmp_gt_i32_e64 s[0:1], s0, v196
	v_mov_b32_e32 v63, 0
	v_mov_b32_e32 v69, 0
	v_mov_b32_e32 v0, 0
	s_and_saveexec_b64 s[4:5], s[0:1]
	v_readlane_b32 s40, v254, 24
	v_readlane_b32 s41, v254, 25
	s_cbranch_execz .LBB0_537
	s_setprio 3
	s_ashr_i32 s41, s40, 31
	s_lshl_b64 s[6:7], s[40:41], 17
	s_add_u32 s6, s70, s6
	s_addc_u32 s7, s71, s7
	s_lshl_b32 s11, s10, 2
	s_add_u32 s6, s6, s11
	s_movk_i32 s11, 0x7f
	s_movk_i32 s24, 0x80
	v_and_b32_e32 v0, 0x7f, v196
	v_bitop3_b32 v1, v196, s11, v196 bitop3:0xc
	v_cmp_gt_u32_e32 vcc, s24, v196
	s_addc_u32 s7, s7, 0
	s_add_u32 s6, s6, 0xfc00000
	v_cndmask_b32_e32 v63, v1, v0, vcc
	v_ashrrev_i32_e32 v0, 4, v196
	v_and_or_b32 v0, v0, -8, s34
	v_or_b32_e32 v4, 4, v0
	v_ashrrev_i32_e32 v5, 31, v4
	s_addc_u32 s7, s7, 0
	v_lshlrev_b64 v[4:5], 13, v[4:5]
	v_lshlrev_b32_e32 v2, 2, v63
	v_mov_b32_e32 v3, 0
	v_lshl_add_u64 v[4:5], s[6:7], 0, v[4:5]
	v_lshl_add_u64 v[4:5], v[4:5], 0, v[2:3]
	global_load_dword v4, v[4:5], off
	v_ashrrev_i32_e32 v1, 31, v0
	v_lshlrev_b64 v[0:1], 13, v[0:1]
	v_lshl_add_u64 v[0:1], s[6:7], 0, v[0:1]
	v_lshl_add_u64 v[0:1], v[0:1], 0, v[2:3]
	global_load_dword v0, v[0:1], off
	s_waitcnt vmcnt(1)
	s_nop 1
	v_add_f32_dpp v4, v4, v4 row_shr:1 row_mask:0xf bank_mask:0xf
	s_nop 1
	v_add_f32_dpp v4, v4, v4 row_shr:2 row_mask:0xf bank_mask:0xf
	s_nop 1
	v_add_f32_dpp v4, v4, v4 row_shr:4 row_mask:0xf bank_mask:0xf
	s_nop 1
	v_add_f32_dpp v4, v4, v4 row_shr:8 row_mask:0xf bank_mask:0xf
	s_nop 1
	v_add_f32_dpp v4, v4, v4 row_bcast:15 row_mask:0xa bank_mask:0xf
	s_nop 1
	v_add_f32_dpp v4, v4, v4 row_bcast:31 row_mask:0xc bank_mask:0xf
	v_mov_b32_e32 v69, v4
	v_cmp_eq_u32_e32 vcc, 63, v197
	s_and_saveexec_b64 s[6:7], vcc
	v_lshl_add_u32 v1, v68, 2, 0
	v_add_u32_e32 v1, 0x21800, v1
	ds_write_b32 v1, v69
	s_or_b64 exec, exec, s[6:7]
.LBB0_537:
	s_setprio 0
	s_or_b64 exec, exec, s[4:5]
	s_lshl_b32 s53, s40, 11
	s_or_b32 s4, s10, s53
	s_ashr_i32 s4, s4, 6
	s_or_b32 s4, s4, s34
	s_ashr_i32 s5, s4, 31
	s_lshl_b64 s[4:5], s[4:5], 17
	v_readlane_b32 s6, v254, 35
	v_readlane_b32 s7, v254, 36
	s_add_u32 s44, s6, s4
	s_addc_u32 s45, s7, s5
	s_lshl_b32 s4, s40, 3
	s_lshl_b32 s5, s34, 1
	s_or_b32 s50, s5, s4
	v_ashrrev_i32_e32 v62, 8, v196
	v_add_u32_e32 v1, s50, v62
	v_add_u32_e32 v38, 0x200, v196
	v_lshl_or_b32 v2, v1, 4, s52
	v_bfe_u32 v34, v196, 7, 2
	v_ashrrev_i32_e32 v39, 9, v38
	v_ashrrev_i32_e32 v3, 31, v2
	v_bfe_u32 v198, v196, 6, 1
	v_lshlrev_b32_e32 v199, 1, v34
	v_lshlrev_b32_e32 v6, 4, v39
	v_lshlrev_b64 v[2:3], 10, v[2:3]
	v_mov_b32_e32 v1, 2
	v_or3_b32 v6, v199, v6, v198
	v_lshl_add_u64 v[2:3], s[16:17], 0, v[2:3]
	v_lshlrev_b32_sdwa v60, v1, v196 dst_sel:DWORD dst_unused:UNUSED_PAD src0_sel:DWORD src1_sel:BYTE_0
	v_mov_b32_e32 v61, 0
	v_lshl_or_b32 v6, v6, 6, v197
	v_lshl_add_u64 v[2:3], v[2:3], 0, v[60:61]
	v_ashrrev_i32_e32 v7, 31, v6
	global_load_dword v1, v[2:3], off
	v_ashrrev_i32_e32 v35, 9, v196
	v_lshl_add_u64 v[6:7], v[6:7], 4, s[44:45]
	global_load_dwordx4 v[6:9], v[6:7], off nt
	v_lshlrev_b32_e32 v2, 4, v35
	v_or3_b32 v2, v199, v2, v198
	v_lshl_or_b32 v2, v2, 6, v197
	v_ashrrev_i32_e32 v3, 31, v2
	v_lshl_add_u64 v[2:3], v[2:3], 4, s[44:45]
	global_load_dwordx4 v[2:5], v[2:3], off nt
	v_add_u32_e32 v40, 0x400, v196
	v_ashrrev_i32_e32 v41, 9, v40
	v_lshlrev_b32_e32 v10, 4, v41
	v_or3_b32 v10, v199, v10, v198
	v_lshl_or_b32 v10, v10, 6, v197
	v_ashrrev_i32_e32 v11, 31, v10
	v_lshl_add_u64 v[10:11], v[10:11], 4, s[44:45]
	v_add_u32_e32 v42, 0x600, v196
	global_load_dwordx4 v[10:13], v[10:11], off nt
	v_ashrrev_i32_e32 v43, 9, v42
	v_lshlrev_b32_e32 v14, 4, v43
	v_or3_b32 v14, v199, v14, v198
	v_lshl_or_b32 v14, v14, 6, v197
	v_ashrrev_i32_e32 v15, 31, v14
	v_lshl_add_u64 v[14:15], v[14:15], 4, s[44:45]
	v_add_u32_e32 v44, 0x800, v196
	global_load_dwordx4 v[14:17], v[14:15], off nt
	v_ashrrev_i32_e32 v45, 9, v44
	v_lshlrev_b32_e32 v18, 4, v45
	v_or3_b32 v18, v199, v18, v198
	v_lshl_or_b32 v18, v18, 6, v197
	v_ashrrev_i32_e32 v19, 31, v18
	v_lshl_add_u64 v[18:19], v[18:19], 4, s[44:45]
	v_add_u32_e32 v46, 0xa00, v196
	global_load_dwordx4 v[18:21], v[18:19], off nt
	v_ashrrev_i32_e32 v47, 9, v46
	v_lshlrev_b32_e32 v22, 4, v47
	v_or3_b32 v22, v199, v22, v198
	v_lshl_or_b32 v22, v22, 6, v197
	v_ashrrev_i32_e32 v23, 31, v22
	v_lshl_add_u64 v[22:23], v[22:23], 4, s[44:45]
	v_add_u32_e32 v48, 0xc00, v196
	global_load_dwordx4 v[22:25], v[22:23], off nt
	v_ashrrev_i32_e32 v49, 9, v48
	v_lshlrev_b32_e32 v26, 4, v49
	v_or3_b32 v26, v199, v26, v198
	v_lshl_or_b32 v26, v26, 6, v197
	v_ashrrev_i32_e32 v27, 31, v26
	v_lshl_add_u64 v[26:27], v[26:27], 4, s[44:45]
	v_add_u32_e32 v50, 0xe00, v196
	global_load_dwordx4 v[26:29], v[26:27], off nt
; #define LAS __attribute__((address_space(3)))
; __device__ void passB_unit(const Params& p, LAS unsigned char* lds, int u, bool do_store = true) {
;     ...
;     { const int d = tid >> 8, k = tid & 255; nvec[tid] = ((const float*)(p.ws + OFF_NST))[(size_t)((sid0 + d) * 16 + c) * 256 + k]; }
; #pragma unroll
;     for (int i = 0; i < 8; ++i) { const int id = tid + 512 * i; const int w = id >> 9, m = (id >> 7) & 3, bj = (id >> 6) & 1, ln = id & 63;
;         *(LAS u32x4*)(Qs + ((w >> 2) * 64 + m * 16 + (ln & 15)) * 264 + bj * 128 + (w & 3) * 32 + (ln >> 4) * 8) = __builtin_nontemporal_load((const u32x4*)(Qg + (size_t)((w * 16 + m * 2 + bj) * 64 + ln) * 8)); }
;     __syncthreads();
;     float sc_a = 0.f, sc_pm = 0.f;
;     if (tid < 256) { if (wid & 1) sc_b += wtot[wid - 1];
;         sc_a = sc_li - sc_b; float pm = sc_a;
; #pragma unroll
;         for (int off = 1; off < 64; off <<= 1) { const float n = __shfl_up(pm, off); pm = (lane >= off) ? fmaxf(pm, n) : pm; }
;         sc_pm = pm; if (lane == 63) wmax[wid] = pm; }
;     __syncthreads();
;     const int wt2 = wid >> 2, w4 = wid & 3;
;     const bf16_t* Kg = (const bf16_t*)(p.ws + OFF_K) + (size_t)((b * 16 + c) * 4 + h) * 32768 + (size_t)(w4 * 2 * 8) * 512 + (fr * 4 + fq) * 8;
;     bf16x8 kfa[8][2];
; #pragma unroll
;     for (int ks = 0; ks < 8; ++ks)
; #pragma unroll
;         for (int nt = 0; nt < 2; ++nt) kfa[ks][nt] = *(const bf16x8*)(Kg + (size_t)(nt * 8 + ks) * 512);
	v_ashrrev_i32_e32 v51, 9, v50
	v_lshlrev_b32_e32 v30, 4, v51
	v_or3_b32 v30, v199, v30, v198
	v_lshl_or_b32 v30, v30, 6, v197
	v_ashrrev_i32_e32 v31, 31, v30
	v_lshl_add_u64 v[30:31], v[30:31], 4, s[44:45]
	global_load_dwordx4 v[30:33], v[30:31], off nt
	s_lshl_b32 s62, s40, 4
	s_or_b32 s62, s62, s52
	s_lshl_b32 s62, s62, 2
	s_or_b32 s62, s62, s34
	s_ashr_i32 s63, s62, 31
	s_lshl_b64 s[62:63], s[62:63], 16
	s_add_u32 s62, s30, s62
	s_addc_u32 s63, s31, s63
	s_add_u32 s62, s62, 0x1000
	s_addc_u32 s63, s63, 0
	v_and_b32_e32 v160, 15, v196
	v_lshrrev_b32_e32 v161, 4, v197
	v_lshlrev_b32_e32 v160, 5, v160
	v_lshl_or_b32 v160, v161, 3, v160
	v_lshlrev_b32_e32 v160, 1, v160
	v_bfe_u32 v161, v196, 6, 2
	v_lshl_add_u32 v160, v161, 14, v160
	v_mov_b32_e32 v161, 0
	v_lshl_add_u64 v[162:163], s[62:63], 0, v[160:161]
	s_add_u32 s62, s62, 0x2000
	s_addc_u32 s63, s63, 0
	v_lshl_add_u64 v[164:165], s[62:63], 0, v[160:161]
	global_load_dwordx4 v[94:97], v[162:163], off offset:-4096
	global_load_dwordx4 v[98:101], v[162:163], off offset:-3072
	global_load_dwordx4 v[102:105], v[164:165], off offset:-4096
	global_load_dwordx4 v[106:109], v[164:165], off offset:-3072
	global_load_dwordx4 v[110:113], v[162:163], off offset:-2048
	global_load_dwordx4 v[114:117], v[162:163], off offset:-1024
	global_load_dwordx4 v[118:121], v[164:165], off offset:-2048
	global_load_dwordx4 v[122:125], v[164:165], off offset:-1024
	global_load_dwordx4 v[126:129], v[162:163], off
	global_load_dwordx4 v[130:133], v[162:163], off offset:1024
	global_load_dwordx4 v[134:137], v[164:165], off
	global_load_dwordx4 v[138:141], v[164:165], off offset:1024
	global_load_dwordx4 v[142:145], v[162:163], off offset:2048
	global_load_dwordx4 v[146:149], v[162:163], off offset:3072
	global_load_dwordx4 v[150:153], v[164:165], off offset:2048
	global_load_dwordx4 v[154:157], v[164:165], off offset:3072
	v_lshl_add_u32 v92, v196, 2, 0
	v_lshrrev_b32_e32 v36, 1, v196
	v_add_u32_e32 v37, 0x23400, v92
	v_and_b32_e32 v201, 15, v196
	v_lshlrev_b32_e32 v202, 4, v34
	v_lshlrev_b32_e32 v203, 8, v198
	v_add_u32_e32 v34, 0, v203
	s_movk_i32 s6, 0x210
	v_and_b32_e32 v60, 64, v196
	v_mov_b32_e32 v70, v61
	s_waitcnt vmcnt(24)
	ds_write_b32 v37, v1
	v_and_b32_e32 v1, 24, v36
	v_ashrrev_i32_e32 v36, 5, v196
	v_and_b32_e32 v36, 0xfffffc0, v36
	v_or3_b32 v36, v36, v202, v201
	v_mad_u64_u32 v[36:37], s[4:5], v36, s6, v[34:35]
	v_lshlrev_b32_e32 v35, 6, v35
	v_and_b32_e32 v35, 0xc0, v35
	v_lshlrev_b32_e32 v200, 1, v1
	v_add3_u32 v1, v36, v35, v200
	s_waitcnt vmcnt(22)
	ds_write_b128 v1, v[2:5]
	v_ashrrev_i32_e32 v1, 5, v38
	v_and_b32_e32 v1, 0xfffffc0, v1
	v_or3_b32 v1, v202, v1, v201
	v_mad_u64_u32 v[2:3], s[4:5], v1, s6, v[34:35]
	v_lshlrev_b32_e32 v1, 6, v39
	v_and_b32_e32 v1, 0xc0, v1
	v_add3_u32 v1, v2, v1, v200
	ds_write_b128 v1, v[6:9]
	v_ashrrev_i32_e32 v1, 5, v40
	v_and_b32_e32 v1, 0xfffffc0, v1
	v_or3_b32 v1, v202, v1, v201
	v_mad_u64_u32 v[2:3], s[4:5], v1, s6, v[34:35]
	v_lshlrev_b32_e32 v1, 6, v41
	v_and_b32_e32 v1, 0xc0, v1
	v_add3_u32 v1, v2, v1, v200
	s_waitcnt vmcnt(21)
	ds_write_b128 v1, v[10:13]
	v_ashrrev_i32_e32 v1, 5, v42
	v_and_b32_e32 v1, 0xfffffc0, v1
	v_or3_b32 v1, v202, v1, v201
	v_mad_u64_u32 v[2:3], s[4:5], v1, s6, v[34:35]
	v_lshlrev_b32_e32 v1, 6, v43
	v_and_b32_e32 v1, 0xc0, v1
	v_add3_u32 v1, v2, v1, v200
	s_waitcnt vmcnt(20)
	ds_write_b128 v1, v[14:17]
	v_ashrrev_i32_e32 v1, 5, v44
	v_and_b32_e32 v1, 0xfffffc0, v1
	v_or3_b32 v1, v202, v1, v201
	v_mad_u64_u32 v[2:3], s[4:5], v1, s6, v[34:35]
	v_lshlrev_b32_e32 v1, 6, v45
	v_and_b32_e32 v1, 0xc0, v1
	v_add3_u32 v1, v2, v1, v200
	s_waitcnt vmcnt(19)
	ds_write_b128 v1, v[18:21]
	v_ashrrev_i32_e32 v1, 5, v46
	v_and_b32_e32 v1, 0xfffffc0, v1
	v_or3_b32 v1, v202, v1, v201
	v_mad_u64_u32 v[2:3], s[4:5], v1, s6, v[34:35]
	v_lshlrev_b32_e32 v1, 6, v47
	v_and_b32_e32 v1, 0xc0, v1
	v_add3_u32 v1, v2, v1, v200
	s_waitcnt vmcnt(18)
	ds_write_b128 v1, v[22:25]
	v_ashrrev_i32_e32 v1, 5, v48
	v_and_b32_e32 v1, 0xfffffc0, v1
	v_or3_b32 v1, v202, v1, v201
	v_mad_u64_u32 v[2:3], s[4:5], v1, s6, v[34:35]
	v_lshlrev_b32_e32 v1, 6, v49
	v_and_b32_e32 v1, 0xc0, v1
	v_add3_u32 v1, v2, v1, v200
	s_waitcnt vmcnt(17)
	ds_write_b128 v1, v[26:29]
	v_ashrrev_i32_e32 v1, 5, v50
	v_and_b32_e32 v1, 0xfffffc0, v1
	v_or3_b32 v1, v202, v1, v201
	v_mad_u64_u32 v[2:3], s[4:5], v1, s6, v[34:35]
	v_lshlrev_b32_e32 v1, 6, v51
	v_and_b32_e32 v1, 0xc0, v1
	v_add3_u32 v1, v2, v1, v200
	s_waitcnt vmcnt(16)
	ds_write_b128 v1, v[30:33]
	s_waitcnt lgkmcnt(0)
	s_barrier
	s_and_saveexec_b64 s[6:7], s[0:1]
	s_cbranch_execz .LBB0_543
	s_setprio 3
	v_cmp_ne_u32_e32 vcc, 0, v60
	s_and_saveexec_b64 s[4:5], vcc
	s_cbranch_execz .LBB0_540
	v_lshlrev_b32_e32 v1, 2, v68
	s_add_i32 s10, 0, 0x21800
	v_add3_u32 v1, s10, v1, -4
	ds_read_b32 v1, v1
	s_waitcnt lgkmcnt(0)
	v_add_f32_e32 v69, v69, v1

; __device__ void passB_unit(const Params& p, LAS unsigned char* lds, int u, bool do_store = true) {
;     ...
;     __syncthreads();
;     const int wt2 = wid >> 2, w4 = wid & 3;
;     const bf16_t* Kg = (const bf16_t*)(p.ws + OFF_K) + (size_t)((b * 16 + c) * 4 + h) * 32768 + (size_t)(w4 * 2 * 8) * 512 + (fr * 4 + fq) * 8;
;     bf16x8 kfa[8][2];
; #pragma unroll
;     for (int ks = 0; ks < 8; ++ks)
; #pragma unroll
;         for (int nt = 0; nt < 2; ++nt) kfa[ks][nt] = *(const bf16x8*)(Kg + (size_t)(nt * 8 + ks) * 512);
;     if (tid < 256) { const int d = tid >> 7, t = sc_t; if (wid & 1) sc_pm = fmaxf(sc_pm, wmax[wid - 1]);
;         const float mc = ((const float*)(p.ws + OFF_MST))[(sid0 + d) * 16 + c];
;         const float Mt = fmaxf(mc, sc_pm); const int dt = d * 128 + t;
.LBB0_543:
	s_setprio 0
	s_or_b64 exec, exec, s[6:7]
	s_lshl_b32 s56, s40, 4
	s_or_b32 s42, s56, s52
	s_lshl_b32 s4, s42, 2
	s_or_b32 s4, s4, s34
	s_ashr_i32 s5, s4, 31
	s_lshl_b64 s[4:5], s[4:5], 16
	v_lshrrev_b32_e32 v93, 4, v197
	v_bfe_u32 v223, v196, 6, 2
	s_add_u32 s4, s30, s4
	v_lshlrev_b32_e32 v2, 5, v201
	s_addc_u32 s5, s31, s5
	v_lshlrev_b32_e32 v88, 14, v223
	v_mov_b32_e32 v89, 0
	v_lshl_or_b32 v2, v93, 3, v2
	v_lshl_add_u64 v[0:1], s[4:5], 0, v[88:89]
	v_lshlrev_b32_e32 v90, 1, v2
	v_mov_b32_e32 v91, v89
	v_lshl_add_u64 v[0:1], v[0:1], 0, v[90:91]
	s_movk_i32 s4, 0x2000
	v_add_co_u32_e32 v2, vcc, s4, v0
	s_movk_i32 s4, 0x1000
	s_nop 0
	v_addc_co_u32_e32 v3, vcc, 0, v1, vcc
	s_waitcnt lgkmcnt(0)
	s_barrier
	s_waitcnt vmcnt(0)
	v_mov_b32_e32 v52, v94
	v_mov_b32_e32 v53, v95
	v_mov_b32_e32 v54, v96
	v_mov_b32_e32 v55, v97
	v_mov_b32_e32 v44, v98
	v_mov_b32_e32 v45, v99
	v_mov_b32_e32 v46, v100
	v_mov_b32_e32 v47, v101
	v_mov_b32_e32 v56, v102
	v_mov_b32_e32 v57, v103
	v_mov_b32_e32 v58, v104
	v_mov_b32_e32 v59, v105
	v_mov_b32_e32 v48, v106
	v_mov_b32_e32 v49, v107
	v_mov_b32_e32 v50, v108
	v_mov_b32_e32 v51, v109
	v_mov_b32_e32 v36, v110
	v_mov_b32_e32 v37, v111
	v_mov_b32_e32 v38, v112
	v_mov_b32_e32 v39, v113
	v_mov_b32_e32 v28, v114
	v_mov_b32_e32 v29, v115
	v_mov_b32_e32 v30, v116
	v_mov_b32_e32 v31, v117
	v_mov_b32_e32 v40, v118
	v_mov_b32_e32 v41, v119
	v_mov_b32_e32 v42, v120
	v_mov_b32_e32 v43, v121
	v_mov_b32_e32 v32, v122
	v_mov_b32_e32 v33, v123
	v_mov_b32_e32 v34, v124
	v_mov_b32_e32 v35, v125
	v_mov_b32_e32 v20, v126
	v_mov_b32_e32 v21, v127
	v_mov_b32_e32 v22, v128
	v_mov_b32_e32 v23, v129
	v_mov_b32_e32 v12, v130
	v_mov_b32_e32 v13, v131
	v_mov_b32_e32 v14, v132
	v_mov_b32_e32 v15, v133
	v_mov_b32_e32 v24, v134
	v_mov_b32_e32 v25, v135
	v_mov_b32_e32 v26, v136
	v_mov_b32_e32 v27, v137
	v_mov_b32_e32 v16, v138
	v_mov_b32_e32 v17, v139
	v_mov_b32_e32 v18, v140
	v_mov_b32_e32 v19, v141
	v_mov_b32_e32 v8, v142
	v_mov_b32_e32 v9, v143
	v_mov_b32_e32 v10, v144
	v_mov_b32_e32 v11, v145
	v_mov_b32_e32 v0, v146
	v_mov_b32_e32 v1, v147
	v_mov_b32_e32 v2, v148
	v_mov_b32_e32 v3, v149
	v_mov_b32_e32 v4, v150
	v_mov_b32_e32 v5, v151
	v_mov_b32_e32 v6, v152
	v_mov_b32_e32 v7, v153
	v_mov_b32_e32 v64, v154
	v_mov_b32_e32 v65, v155
	v_mov_b32_e32 v66, v156
	v_mov_b32_e32 v67, v157
	s_and_saveexec_b64 s[4:5], s[0:1]
	s_cbranch_execz .LBB0_549
	s_setprio 3
	v_cmp_ne_u32_e32 vcc, 0, v60
	s_and_saveexec_b64 s[6:7], vcc
	s_cbranch_execz .LBB0_546
	v_lshlrev_b32_e32 v60, 2, v68
	s_add_i32 s10, 0, 0x21820
	v_add3_u32 v60, s10, v60, -4
	ds_read_b32 v60, v60
	v_max_f32_e32 v68, v70, v70
	s_waitcnt lgkmcnt(0)
	v_max_f32_e32 v60, v60, v60
	v_max_f32_e32 v70, v68, v60

; #define LAS __attribute__((address_space(3)))
; __device__ void passB_unit(const Params& p, LAS unsigned char* lds, int u, bool do_store = true) {
;     ...
;         f32x4 sacc[4][2];
; #pragma unroll
;         for (int mt = 0; mt < 4; ++mt)
; #pragma unroll
;             for (int nt = 0; nt < 2; ++nt) sacc[mt][nt] = (f32x4){0.f, 0.f, 0.f, 0.f};
; #pragma unroll
;         for (int ks = 0; ks < 8; ++ks) { bf16x8 qf[4];
; #pragma unroll
;             for (int mt = 0; mt < 4; ++mt) qf[mt] = *(const LAS bf16x8*)(Qs + (wt2 * 64 + mt * 16 + fr) * 264 + ks * 32 + fq * 8);
; #pragma unroll
;             for (int mt = 0; mt < 4; ++mt)
; #pragma unroll
;                 for (int nt = 0; nt < 2; ++nt) sacc[mt][nt] = __builtin_amdgcn_mfma_f32_16x16x32_bf16(kfa[ks][nt], qf[mt], sacc[mt][nt], 0, 0, 0); }
.LBB0_549:
	s_setprio 0
	s_or_b64 exec, exec, s[4:5]
	v_lshl_or_b32 v211, v62, 6, v201
	s_movk_i32 s4, 0x210
	v_and_b32_e32 v116, 48, v196
	v_mul_lo_u32 v210, v211, s4
	v_add_u32_e32 v91, 0, v116
	v_add_u32_e32 v253, 0x2100, v210
	v_add_u32_e32 v252, 0x4200, v210
	v_add_u32_e32 v227, 0x6300, v210
	v_add_u32_e32 v217, v91, v210
	v_add_u32_e32 v114, v91, v253
	v_add_u32_e32 v115, v91, v252
	v_add_u32_e32 v91, v91, v227
	s_waitcnt lgkmcnt(0)
	s_barrier
	ds_read_b128 v[60:63], v217
	ds_read_b128 v[68:71], v217 offset:64
	ds_read_b128 v[76:79], v114
	ds_read_b128 v[80:83], v114 offset:64
	ds_read_b128 v[94:97], v115
	ds_read_b128 v[98:101], v115 offset:64
	ds_read_b128 v[106:109], v91
	ds_read_b128 v[110:113], v91 offset:64
	s_waitcnt vmcnt(15) lgkmcnt(7)
	v_mfma_f32_16x16x32_bf16 v[72:75], v[52:55], v[60:63], 0
	s_cmp_lt_i32 s50, 32
	s_cselect_b32 s57, s69, s13
	s_cselect_b32 s58, s68, s12
	s_waitcnt vmcnt(13)
	v_mfma_f32_16x16x32_bf16 v[60:63], v[56:59], v[60:63], 0
	s_lshl_b32 s4, s50, 4
	s_and_b32 s59, s4, 0x1e0
	s_or_b32 s4, s59, s52
	s_waitcnt lgkmcnt(5)
	v_mfma_f32_16x16x32_bf16 v[84:87], v[52:55], v[76:79], 0
	s_lshl_b32 s4, s4, 17
	s_add_u32 s4, s58, s4
	s_addc_u32 s5, s57, 0
	v_mfma_f32_16x16x32_bf16 v[76:79], v[56:59], v[76:79], 0
	v_lshlrev_b32_e32 v89, 13, v223
	s_waitcnt lgkmcnt(3)
	v_mfma_f32_16x16x32_bf16 v[102:105], v[52:55], v[94:97], 0
	v_mfma_f32_16x16x32_bf16 v[94:97], v[56:59], v[94:97], 0
	s_waitcnt lgkmcnt(1)
	v_mfma_f32_16x16x32_bf16 v[52:55], v[52:55], v[106:109], 0
	v_mfma_f32_16x16x32_bf16 v[56:59], v[56:59], v[106:109], 0
	v_mfma_f32_16x16x32_bf16 v[72:75], v[44:47], v[68:71], v[72:75]
	s_waitcnt vmcnt(12)
	v_mfma_f32_16x16x32_bf16 v[60:63], v[48:51], v[68:71], v[60:63]
	v_mfma_f32_16x16x32_bf16 v[68:71], v[44:47], v[80:83], v[84:87]
	v_mfma_f32_16x16x32_bf16 v[76:79], v[48:51], v[80:83], v[76:79]
	v_mfma_f32_16x16x32_bf16 v[80:83], v[44:47], v[98:101], v[102:105]
	v_mfma_f32_16x16x32_bf16 v[84:87], v[48:51], v[98:101], v[94:97]
	s_waitcnt lgkmcnt(0)
	v_mfma_f32_16x16x32_bf16 v[44:47], v[44:47], v[110:113], v[52:55]
	v_mfma_f32_16x16x32_bf16 v[48:51], v[48:51], v[110:113], v[56:59]
	s_nop 1
	ds_read_b128 v[52:55], v217 offset:128
	ds_read_b128 v[56:59], v217 offset:192
	s_waitcnt vmcnt(11) lgkmcnt(1)
	v_mfma_f32_16x16x32_bf16 v[72:75], v[36:39], v[52:55], v[72:75]
	s_waitcnt vmcnt(9)
	v_mfma_f32_16x16x32_bf16 v[52:55], v[40:43], v[52:55], v[60:63]
	s_nop 2
	ds_read_b128 v[60:63], v114 offset:128
	ds_read_b128 v[94:97], v114 offset:192
	s_waitcnt lgkmcnt(1)
	v_mfma_f32_16x16x32_bf16 v[68:71], v[36:39], v[60:63], v[68:71]
	v_mfma_f32_16x16x32_bf16 v[60:63], v[40:43], v[60:63], v[76:79]
	s_nop 2
	ds_read_b128 v[76:79], v115 offset:128
	ds_read_b128 v[98:101], v115 offset:192
	s_waitcnt lgkmcnt(1)
	v_mfma_f32_16x16x32_bf16 v[80:83], v[36:39], v[76:79], v[80:83]
	v_mfma_f32_16x16x32_bf16 v[76:79], v[40:43], v[76:79], v[84:87]
	s_nop 2
	ds_read_b128 v[84:87], v91 offset:128
	ds_read_b128 v[102:105], v91 offset:192
	s_waitcnt lgkmcnt(1)
	v_mfma_f32_16x16x32_bf16 v[36:39], v[36:39], v[84:87], v[44:47]
	v_mfma_f32_16x16x32_bf16 v[40:43], v[40:43], v[84:87], v[48:51]
	v_mfma_f32_16x16x32_bf16 v[44:47], v[28:31], v[56:59], v[72:75]
	s_waitcnt vmcnt(8)
	v_mfma_f32_16x16x32_bf16 v[48:51], v[32:35], v[56:59], v[52:55]
	v_mfma_f32_16x16x32_bf16 v[52:55], v[28:31], v[94:97], v[68:71]
	v_mfma_f32_16x16x32_bf16 v[56:59], v[32:35], v[94:97], v[60:63]
	v_mfma_f32_16x16x32_bf16 v[60:63], v[28:31], v[98:101], v[80:83]
	v_mfma_f32_16x16x32_bf16 v[68:71], v[32:35], v[98:101], v[76:79]
	s_waitcnt lgkmcnt(0)
	v_mfma_f32_16x16x32_bf16 v[28:31], v[28:31], v[102:105], v[36:39]
	v_mfma_f32_16x16x32_bf16 v[32:35], v[32:35], v[102:105], v[40:43]
	s_nop 1
	ds_read_b128 v[36:39], v217 offset:256
	ds_read_b128 v[40:43], v217 offset:320
	s_waitcnt vmcnt(7) lgkmcnt(1)
	v_mfma_f32_16x16x32_bf16 v[44:47], v[20:23], v[36:39], v[44:47]
	s_waitcnt vmcnt(5)
	v_mfma_f32_16x16x32_bf16 v[36:39], v[24:27], v[36:39], v[48:51]
	s_nop 2
	ds_read_b128 v[48:51], v114 offset:256
	ds_read_b128 v[72:75], v114 offset:320
	s_waitcnt lgkmcnt(1)
	v_mfma_f32_16x16x32_bf16 v[52:55], v[20:23], v[48:51], v[52:55]
	v_mfma_f32_16x16x32_bf16 v[48:51], v[24:27], v[48:51], v[56:59]
	s_nop 2
	ds_read_b128 v[56:59], v115 offset:256
	ds_read_b128 v[76:79], v115 offset:320
	s_waitcnt lgkmcnt(1)
	v_mfma_f32_16x16x32_bf16 v[60:63], v[20:23], v[56:59], v[60:63]
	v_mfma_f32_16x16x32_bf16 v[56:59], v[24:27], v[56:59], v[68:71]
	s_nop 2
	ds_read_b128 v[68:71], v91 offset:256
	ds_read_b128 v[80:83], v91 offset:320
	s_waitcnt lgkmcnt(1)
	v_mfma_f32_16x16x32_bf16 v[20:23], v[20:23], v[68:71], v[28:31]
	v_mfma_f32_16x16x32_bf16 v[24:27], v[24:27], v[68:71], v[32:35]
	v_mfma_f32_16x16x32_bf16 v[28:31], v[12:15], v[40:43], v[44:47]
	s_waitcnt vmcnt(4)
	v_mfma_f32_16x16x32_bf16 v[32:35], v[16:19], v[40:43], v[36:39]
	v_mfma_f32_16x16x32_bf16 v[36:39], v[12:15], v[72:75], v[52:55]
	v_mfma_f32_16x16x32_bf16 v[40:43], v[16:19], v[72:75], v[48:51]
	v_mfma_f32_16x16x32_bf16 v[44:47], v[12:15], v[76:79], v[60:63]
	v_mfma_f32_16x16x32_bf16 v[48:51], v[16:19], v[76:79], v[56:59]
	s_waitcnt lgkmcnt(0)
	v_mfma_f32_16x16x32_bf16 v[12:15], v[12:15], v[80:83], v[20:23]
	v_mfma_f32_16x16x32_bf16 v[16:19], v[16:19], v[80:83], v[24:27]
	s_nop 1
	ds_read_b128 v[20:23], v217 offset:384
	ds_read_b128 v[24:27], v217 offset:448
	ds_read_b128 v[60:63], v114 offset:448
	ds_read_b128 v[52:55], v115 offset:384
	ds_read_b128 v[68:71], v115 offset:448
	s_waitcnt vmcnt(3) lgkmcnt(4)
	v_mfma_f32_16x16x32_bf16 v[28:31], v[8:11], v[20:23], v[28:31]
	ds_read_b128 v[98:101], v91 offset:448
	s_waitcnt vmcnt(1)
; #define LAS __attribute__((address_space(3)))
; __device__ __forceinline__ unsigned cvt_pk_bf16(float lo, float hi) { unsigned r; asm volatile("v_cvt_pk_bf16_f32 %0, %1, %2" : "=v"(r) : "v"(lo), "v"(hi)); return r; }
; __device__ void passB_unit(const Params& p, LAS unsigned char* lds, int u, bool do_store = true) {
;     ...
;         for (int ks = 0; ks < 8; ++ks) { bf16x8 qf[4];
; #pragma unroll
;             for (int mt = 0; mt < 4; ++mt) qf[mt] = *(const LAS bf16x8*)(Qs + (wt2 * 64 + mt * 16 + fr) * 264 + ks * 32 + fq * 8);
; #pragma unroll
;             for (int mt = 0; mt < 4; ++mt)
; #pragma unroll
;                 for (int nt = 0; nt < 2; ++nt) sacc[mt][nt] = __builtin_amdgcn_mfma_f32_16x16x32_bf16(kfa[ks][nt], qf[mt], sacc[mt][nt], 0, 0, 0); }
;         PB_ISSUE(0); PB_ISSUE(1);
;         __builtin_amdgcn_sched_barrier(0);
; #pragma unroll
;         for (int mt = 0; mt < 4; ++mt) { const int t = wt2 * 64 + mt * 16 + fr; const float Mf = MA[t], Mb = MA[128 + t]; float rf = 0.f, rb = 0.f;
; #pragma unroll
;             for (int nt = 0; nt < 2; ++nt) { const int s0 = w4 * 32 + nt * 16 + fq * 4; float pf[4], pb[4];
; #pragma unroll
;                 for (int r = 0; r < 4; ++r) { const int s = s0 + r; const float val = sacc[mt][nt][r];
;                     const float ef = __expf(fminf(aA[s] - Mf, 0.f)), eb = __expf(fminf(aA[128 + s] - Mb, 0.f));
;                     pf[r] = (s <= t) ? val * ef : 0.f; pb[r] = (s >= t) ? val * eb : 0.f; rf += pf[r]; rb += pb[r]; }
;                 u32x2 wf, wb; wf.x = cvt_pk_bf16(pf[0], pf[1]); wf.y = cvt_pk_bf16(pf[2], pf[3]); wb.x = cvt_pk_bf16(pb[0], pb[1]); wb.y = cvt_pk_bf16(pb[2], pb[3]);
;                 *(LAS u32x2*)(Pd + t * 136 + s0) = wf; *(LAS u32x2*)(Pd + 128 * 136 + t * 136 + s0) = wb; }
	v_mfma_f32_16x16x32_bf16 v[20:23], v[4:7], v[20:23], v[32:35]
	s_nop 2
	ds_read_b128 v[32:35], v114 offset:384
	s_waitcnt lgkmcnt(0)
	v_mfma_f32_16x16x32_bf16 v[36:39], v[8:11], v[32:35], v[36:39]
	v_mfma_f32_16x16x32_bf16 v[32:35], v[4:7], v[32:35], v[40:43]
	s_nop 2
	ds_read_b128 v[40:43], v91 offset:384
	v_mfma_f32_16x16x32_bf16 v[72:75], v[8:11], v[52:55], v[44:47]
	s_waitcnt lgkmcnt(0)
	v_mfma_f32_16x16x32_bf16 v[12:15], v[8:11], v[40:43], v[12:15]
	v_mov_b32_e32 v9, 0
	v_lshlrev_b32_e32 v8, 15, v223
	v_lshl_add_u64 v[10:11], s[4:5], 0, v[8:9]
	v_mov_b32_e32 v91, v9
	v_lshl_add_u64 v[140:141], v[10:11], 0, v[90:91]
	s_movk_i32 s4, 0x2000
	v_mfma_f32_16x16x32_bf16 v[94:97], v[4:7], v[52:55], v[48:51]
	v_mfma_f32_16x16x32_bf16 v[102:105], v[4:7], v[40:43], v[16:19]
	v_add_co_u32_e32 v4, vcc, s4, v140
	s_movk_i32 s4, 0x3000
	s_nop 0
	v_addc_co_u32_e32 v5, vcc, 0, v141, vcc
	v_add_co_u32_e32 v114, vcc, s4, v140
	s_movk_i32 s4, 0x1000
	s_nop 0
	v_addc_co_u32_e32 v115, vcc, 0, v141, vcc
	v_add_co_u32_e32 v6, vcc, s4, v140
	v_mfma_f32_16x16x32_bf16 v[106:109], v[0:3], v[24:27], v[28:31]
	s_nop 0
	v_addc_co_u32_e32 v7, vcc, 0, v141, vcc
	global_load_dwordx4 v[56:59], v[140:141], off nt
	global_load_dwordx4 v[48:51], v[140:141], off offset:1024 nt
	global_load_dwordx4 v[52:55], v[4:5], off offset:1024 nt
	global_load_dwordx4 v[40:43], v[4:5], off offset:2048 nt
	s_waitcnt vmcnt(4)
	v_mfma_f32_16x16x32_bf16 v[110:113], v[64:67], v[24:27], v[20:23]
	v_mfma_f32_16x16x32_bf16 v[84:87], v[0:3], v[60:63], v[36:39]
	v_mfma_f32_16x16x32_bf16 v[80:83], v[64:67], v[60:63], v[32:35]
	global_load_dwordx4 v[44:47], v[140:141], off offset:2048 nt
	s_nop 1
	global_load_dwordx4 v[32:35], v[140:141], off offset:3072 nt
	global_load_dwordx4 v[36:39], v[4:5], off offset:3072 nt
	global_load_dwordx4 v[24:27], v[6:7], off nt
	global_load_dwordx4 v[28:31], v[114:115], off nt
	global_load_dwordx4 v[16:19], v[114:115], off offset:1024 nt
	global_load_dwordx4 v[20:23], v[6:7], off offset:1024 nt
	global_load_dwordx4 v[8:11], v[6:7], off offset:2048 nt
	v_mfma_f32_16x16x32_bf16 v[76:79], v[0:3], v[68:71], v[72:75]
	v_mfma_f32_16x16x32_bf16 v[72:75], v[64:67], v[68:71], v[94:97]
	v_mfma_f32_16x16x32_bf16 v[68:71], v[0:3], v[98:101], v[12:15]
	global_load_dwordx4 v[60:63], v[114:115], off offset:-4096 nt
	s_nop 0
	global_load_dwordx4 v[4:7], v[6:7], off offset:3072 nt
	s_nop 0
	global_load_dwordx4 v[12:15], v[114:115], off offset:2048 nt
	global_load_dwordx4 v[0:3], v[114:115], off offset:3072 nt
	v_mfma_f32_16x16x32_bf16 v[64:67], v[64:67], v[98:101], v[102:105]
	v_lshlrev_b32_e32 v212, 2, v93
	v_lshl_or_b32 v91, v223, 5, v212
	v_lshl_add_u32 v93, v211, 2, 0
	s_add_i32 s51, 0, 0x22000
	v_add_u32_e32 v93, 0x22400, v93
	v_lshl_add_u32 v96, v91, 2, s51
	ds_read2st64_b32 v[114:115], v93 offset1:2
	ds_read_b128 v[100:103], v96
	ds_read_b128 v[118:121], v96 offset:512
	s_movk_i32 s6, 0x88
	v_cmp_gt_i32_e32 vcc, v91, v211
	v_mul_lo_u32 v104, v211, s6
	s_waitcnt lgkmcnt(1)
	v_sub_f32_e32 v94, v100, v114
	v_min_f32_e32 v94, 0, v94
	s_waitcnt lgkmcnt(0)
	v_sub_f32_e32 v95, v118, v115
	v_mul_f32_e32 v94, 0x3fb8aa3b, v94
	v_min_f32_e32 v95, 0, v95
	v_sub_f32_e32 v99, v119, v115
	v_exp_f32_e32 v94, v94
	v_mul_f32_e32 v95, 0x3fb8aa3b, v95
	v_min_f32_e32 v99, 0, v99
	v_exp_f32_e32 v95, v95
	v_mul_f32_e32 v99, 0x3fb8aa3b, v99
	v_exp_f32_e32 v99, v99
	v_mul_f32_e32 v94, v106, v94
	v_cndmask_b32_e64 v97, v94, 0, vcc
	v_mul_f32_e32 v94, v106, v95
	v_cmp_lt_i32_e64 s[6:7], v91, v211
	v_sub_f32_e32 v98, v101, v114
	v_or_b32_e32 v100, 1, v91
	v_cndmask_b32_e64 v105, v94, 0, s[6:7]
	v_min_f32_e32 v98, 0, v98
	v_mul_f32_e32 v99, v107, v99
	v_cmp_ge_i32_e64 s[10:11], v100, v211
	v_add_f32_e32 v95, 0, v105
	v_mul_f32_e32 v98, 0x3fb8aa3b, v98
	v_cndmask_b32_e64 v101, 0, v99, s[10:11]
	v_exp_f32_e32 v98, v98
	v_add_f32_e32 v118, v95, v101
	v_sub_f32_e32 v95, v102, v114
	v_min_f32_e32 v95, 0, v95
	v_mul_f32_e32 v95, 0x3fb8aa3b, v95
	v_exp_f32_e32 v95, v95
	v_sub_f32_e32 v102, v120, v115
	v_mul_f32_e32 v98, v107, v98
	v_min_f32_e32 v102, 0, v102
	v_add_f32_e32 v94, 0, v97
	v_cndmask_b32_e64 v98, 0, v98, s[6:7]
	v_mul_f32_e32 v102, 0x3fb8aa3b, v102
	v_add_f32_e32 v99, v94, v98
	v_or_b32_e32 v94, 2, v91
	v_exp_f32_e32 v102, v102
	v_mul_f32_e32 v95, v108, v95
	v_cmp_le_i32_e64 s[10:11], v94, v211
	v_lshlrev_b32_e32 v93, 1, v104
	s_add_i32 s46, 0, 0x10800
	v_cndmask_b32_e64 v106, 0, v95, s[10:11]
	v_add_f32_e32 v120, v99, v106
	v_sub_f32_e32 v99, v103, v114
	v_mul_f32_e32 v95, v108, v102
	v_min_f32_e32 v99, 0, v99
	v_sub_f32_e32 v102, v121, v115
	v_mul_f32_e32 v99, 0x3fb8aa3b, v99
	v_min_f32_e32 v102, 0, v102
	v_exp_f32_e32 v99, v99
	v_mul_f32_e32 v102, 0x3fb8aa3b, v102
	v_exp_f32_e32 v102, v102
	v_cmp_ge_i32_e64 s[10:11], v94, v211
	v_mul_f32_e32 v99, v109, v99
	s_add_i32 s48, 0, 0x19000
	v_cndmask_b32_e64 v119, 0, v95, s[10:11]
	v_or_b32_e32 v95, 3, v91
	v_cmp_le_i32_e64 s[10:11], v95, v211
	v_cvt_pk_bf16_f32 v98, v97, v98
	v_add_f32_e32 v97, v118, v119
	v_mbcnt_hi_u32_b32 v204, -1, v158
	v_cndmask_b32_e64 v103, 0, v99, s[10:11]
	v_mul_f32_e32 v99, v109, v102
	v_lshlrev_b32_e32 v102, 1, v91
	v_cmp_ge_i32_e64 s[10:11], v95, v211
	v_add3_u32 v122, s46, v93, v102
	v_add3_u32 v123, s48, v93, v102
	v_or_b32_e32 v93, 16, v91
	v_cndmask_b32_e64 v121, 0, v99, s[10:11]
	v_cvt_pk_bf16_f32 v99, v106, v103
	v_cvt_pk_bf16_f32 v106, v105, v101
	v_cvt_pk_bf16_f32 v107, v119, v121
	ds_write_b64 v122, v[98:99]
	ds_write_b64 v123, v[106:107]
	v_lshl_add_u32 v101, v93, 2, s51
	ds_read_b128 v[106:109], v101
	v_add_f32_e32 v98, v120, v103
	v_add_f32_e32 v97, v97, v121
	ds_read_b128 v[118:121], v101 offset:512
	v_cmp_le_i32_e64 s[10:11], v93, v211
	s_waitcnt lgkmcnt(1)
; #define LAS __attribute__((address_space(3)))
; __device__ __forceinline__ unsigned cvt_pk_bf16(float lo, float hi) { unsigned r; asm volatile("v_cvt_pk_bf16_f32 %0, %1, %2" : "=v"(r) : "v"(lo), "v"(hi)); return r; }
; __device__ void passB_unit(const Params& p, LAS unsigned char* lds, int u, bool do_store = true) {
;     ...
;         for (int mt = 0; mt < 4; ++mt) { const int t = wt2 * 64 + mt * 16 + fr; const float Mf = MA[t], Mb = MA[128 + t]; float rf = 0.f, rb = 0.f;
; #pragma unroll
;             for (int nt = 0; nt < 2; ++nt) { const int s0 = w4 * 32 + nt * 16 + fq * 4; float pf[4], pb[4];
; #pragma unroll
;                 for (int r = 0; r < 4; ++r) { const int s = s0 + r; const float val = sacc[mt][nt][r];
;                     const float ef = __expf(fminf(aA[s] - Mf, 0.f)), eb = __expf(fminf(aA[128 + s] - Mb, 0.f));
;                     pf[r] = (s <= t) ? val * ef : 0.f; pb[r] = (s >= t) ? val * eb : 0.f; rf += pf[r]; rb += pb[r]; }
;                 u32x2 wf, wb; wf.x = cvt_pk_bf16(pf[0], pf[1]); wf.y = cvt_pk_bf16(pf[2], pf[3]); wb.x = cvt_pk_bf16(pb[0], pb[1]); wb.y = cvt_pk_bf16(pb[2], pb[3]);
;                 *(LAS u32x2*)(Pd + t * 136 + s0) = wf; *(LAS u32x2*)(Pd + 128 * 136 + t * 136 + s0) = wb; }
;             rf += __shfl_xor(rf, 16); rf += __shfl_xor(rf, 32); rb += __shfl_xor(rb, 16); rb += __shfl_xor(rb, 32);
;             if (fq == 0) { rsP[w4 * 128 + t] = rf; rsP[512 + w4 * 128 + t] = rb; } }
	v_sub_f32_e32 v99, v106, v114
	v_sub_f32_e32 v106, v107, v114
	v_min_f32_e32 v106, 0, v106
	s_waitcnt lgkmcnt(0)
	v_sub_f32_e32 v107, v119, v115
	v_min_f32_e32 v107, 0, v107
	v_min_f32_e32 v99, 0, v99
	v_sub_f32_e32 v103, v118, v115
	v_mul_f32_e32 v106, 0x3fb8aa3b, v106
	v_mul_f32_e32 v107, 0x3fb8aa3b, v107
	v_mul_f32_e32 v99, 0x3fb8aa3b, v99
	v_min_f32_e32 v103, 0, v103
	v_exp_f32_e32 v106, v106
	v_exp_f32_e32 v107, v107
	v_exp_f32_e32 v99, v99
	v_mul_f32_e32 v103, 0x3fb8aa3b, v103
	v_exp_f32_e32 v103, v103
	v_mul_f32_e32 v106, v111, v106
	v_mul_f32_e32 v107, v111, v107
	v_sub_f32_e32 v108, v108, v114
	v_sub_f32_e32 v111, v120, v115
	v_mul_f32_e32 v99, v110, v99
	v_min_f32_e32 v108, 0, v108
	v_min_f32_e32 v111, 0, v111
	v_cndmask_b32_e64 v105, 0, v99, s[10:11]
	v_mul_f32_e32 v99, v110, v103
	v_cmp_ge_i32_e64 s[10:11], v93, v211
	v_mul_f32_e32 v108, 0x3fb8aa3b, v108
	v_mul_f32_e32 v111, 0x3fb8aa3b, v111
	v_cndmask_b32_e64 v103, 0, v99, s[10:11]
	v_exp_f32_e32 v108, v108
	v_exp_f32_e32 v111, v111
	v_add_f32_e32 v99, v97, v103
	v_or_b32_e32 v97, 17, v91
	v_cmp_le_i32_e64 s[10:11], v97, v211
	v_sub_f32_e32 v109, v109, v114
	v_add_f32_e32 v98, v98, v105
	v_cndmask_b32_e64 v106, 0, v106, s[10:11]
	v_min_f32_e32 v109, 0, v109
	v_cmp_ge_i32_e64 s[10:11], v97, v211
	v_add_f32_e32 v110, v98, v106
	v_or_b32_e32 v98, 18, v91
	v_mul_f32_e32 v108, v112, v108
	v_mul_f32_e32 v111, v112, v111
	v_mul_f32_e32 v109, 0x3fb8aa3b, v109
	v_sub_f32_e32 v112, v121, v115
	v_cndmask_b32_e64 v107, 0, v107, s[10:11]
	v_cmp_le_i32_e64 s[10:11], v98, v211
	v_exp_f32_e32 v109, v109
	v_min_f32_e32 v112, 0, v112
	v_cndmask_b32_e64 v108, 0, v108, s[10:11]
	v_cmp_ge_i32_e64 s[10:11], v98, v211
	v_mul_f32_e32 v112, 0x3fb8aa3b, v112
	v_add_f32_e32 v99, v99, v107
	v_cndmask_b32_e64 v118, 0, v111, s[10:11]
	v_exp_f32_e32 v112, v112
	v_add_f32_e32 v111, v99, v118
	v_or_b32_e32 v99, 19, v91
	v_mul_f32_e32 v109, v113, v109
	v_cmp_le_i32_e64 s[10:11], v99, v211
	v_add_f32_e32 v110, v110, v108
	v_and_b32_e32 v205, 64, v204
	v_cndmask_b32_e64 v109, 0, v109, s[10:11]
	v_mul_f32_e32 v112, v113, v112
	v_cmp_ge_i32_e64 s[10:11], v99, v211
	v_add_f32_e32 v114, v110, v109
	v_xor_b32_e32 v110, 16, v204
	v_add_u32_e32 v115, 64, v205
	v_cndmask_b32_e64 v113, 0, v112, s[10:11]
	v_cmp_lt_i32_e64 s[10:11], v110, v115
	v_add_f32_e32 v120, v111, v113
	v_lshlrev_b32_e32 v216, 9, v223
	v_cndmask_b32_e64 v110, v204, v110, s[10:11]
	v_lshlrev_b32_e32 v225, 2, v110
	v_cvt_pk_bf16_f32 v110, v105, v106
	v_cvt_pk_bf16_f32 v111, v108, v109
	v_cvt_pk_bf16_f32 v112, v103, v107
	v_xor_b32_e32 v103, 32, v204
	v_cmp_lt_i32_e64 s[10:11], v103, v115
	s_waitcnt lgkmcnt(0)
	v_mov_b32_e32 v119, v114
	v_mov_b32_e32 v105, v114
	s_nop 1
	v_permlane16_swap_b32_e32 v119, v105
	v_add_f32_e32 v105, v105, v119
	s_add_i32 s47, 0, 0x23c00
	v_cndmask_b32_e64 v103, v204, v103, s[10:11]
	v_lshlrev_b32_e32 v226, 2, v103
	s_waitcnt lgkmcnt(0)
	v_mov_b32_e32 v107, v120
	v_mov_b32_e32 v119, v120
	s_nop 1
	v_permlane16_swap_b32_e32 v107, v119
	v_add_f32_e32 v107, v107, v119
	v_mov_b32_e32 v106, v105
	s_nop 1
	v_permlane32_swap_b32_e32 v106, v105
	v_mov_b32_e32 v108, v107
	s_nop 1
	v_permlane32_swap_b32_e32 v108, v107
	v_add_u32_e32 v117, s47, v216
	v_cmp_gt_u32_e64 s[4:5], 16, v197
	v_lshl_add_u32 v103, v211, 2, v117
	v_cvt_pk_bf16_f32 v113, v118, v113
	ds_write_b64 v122, v[110:111] offset:32
	ds_write_b64 v123, v[112:113] offset:32
	s_and_saveexec_b64 s[10:11], s[4:5]
	s_cbranch_execz .LBB0_551
	s_waitcnt lgkmcnt(2)
	v_add_f32_e32 v107, v107, v108
	v_add_f32_e32 v105, v105, v106
	ds_write2st64_b32 v103, v105, v107 offset1:8

; #define LAS __attribute__((address_space(3)))
; __device__ void passB_unit(const Params& p, LAS unsigned char* lds, int u, bool do_store = true) {
;     ...
;     LAS float* wtot = lfA; LAS float* wmax = lfA + 8;
;     float sc_b = 0.f, sc_li = 0.f; int sc_t = 0;
;     if (tid < 256) { const int d = tid >> 7, i = tid & 127; sc_t = d ? 127 - i : i;
;         sc_li = GL[(size_t)(d * 8 + h) * 2048 + sc_t]; float inc = GL[(size_t)(d * 8 + 4 + h) * 2048 + sc_t];
; #pragma unroll
;         for (int off = 1; off < 64; off <<= 1) { const float n = __shfl_up(inc, off); inc += (lane >= off) ? n : 0.f; }
;         sc_b = inc; if (lane == 63) wtot[wid] = inc; }
;     { const int d = tid >> 8, k = tid & 255; nvec[tid] = ((const float*)(p.ws + OFF_NST))[(size_t)((sid0 + d) * 16 + c) * 256 + k]; }
;     ...
;         for (int i = 0; i < 8; ++i) { const int id = tid + 512 * i; const int w = id >> 9, m = (id >> 7) & 3, bj = (id >> 6) & 1, ln = id & 63;
;             *(u32x4*)(Qg + (size_t)((w * 16 + m * 2 + bj) * 64 + ln) * 8) = *(const LAS u32x4*)(Pd + ((w >> 2) * 64 + m * 16 + (ln & 15)) * 264 + bj * 128 + (w & 3) * 32 + (ln >> 4) * 8); } }
.LBB0_568:
	v_add_u32_e32 v3, s0, v196
	v_ashrrev_i32_e32 v5, 5, v3
	v_ashrrev_i32_e32 v4, 9, v3
	v_add_u32_e32 v3, 0x200, v3
	v_and_or_b32 v5, v5, s1, v1
	v_lshlrev_b32_e32 v6, 6, v4
	v_lshlrev_b32_e32 v7, 10, v4
	v_ashrrev_i32_e32 v8, 9, v3
	v_ashrrev_i32_e32 v3, 5, v3
	v_mad_u64_u32 v[4:5], s[6:7], v5, s4, v[0:1]
	v_and_b32_e32 v5, 0xc0, v6
	v_and_or_b32 v3, v3, s1, v1
	v_lshlrev_b32_e32 v6, 6, v8
	v_or3_b32 v12, v7, v2, v197
	v_lshlrev_b32_e32 v7, 10, v8
	v_add3_u32 v8, v4, v5, v200
	v_mad_u64_u32 v[4:5], s[6:7], v3, s4, v[0:1]
	v_and_b32_e32 v3, 0xc0, v6
	v_or3_b32 v14, v7, v2, v197
	v_add3_u32 v3, v4, v3, v200
	ds_read_b128 v[4:7], v8
	ds_read_b128 v[8:11], v3
	s_addk_i32 s0, 0x400
	v_ashrrev_i32_e32 v13, 31, v12
	s_cmpk_lg_i32 s0, 0x1000
	v_lshl_add_u64 v[12:13], v[12:13], 4, s[44:45]
	v_ashrrev_i32_e32 v15, 31, v14
	v_lshl_add_u64 v[14:15], v[14:15], 4, s[44:45]
	s_waitcnt lgkmcnt(1)
	global_store_dwordx4 v[12:13], v[4:7], off
	s_waitcnt lgkmcnt(0)
	global_store_dwordx4 v[14:15], v[8:11], off
	s_cbranch_scc1 .LBB0_568
	v_mov_b32_e32 v196, v224
	s_or_b32 s24, s52, 1
	s_movk_i32 s0, 0x100
	s_barrier
	s_lshl_b32 s10, s24, 7
	v_ashrrev_i32_e32 v68, 6, v196
	v_and_b32_e32 v197, 63, v196
	v_cmp_gt_i32_e64 s[0:1], s0, v196
	v_mov_b32_e32 v63, 0
	v_mov_b32_e32 v69, 0
	v_add_u32_e32 v5, -1, v204
	v_add_u32_e32 v4, -2, v204
	v_add_u32_e32 v3, -4, v204
	v_add_u32_e32 v2, -8, v204
	v_add_u32_e32 v1, -16, v204
	v_subrev_u32_e32 v0, 32, v204
	v_mov_b32_e32 v6, 0
	s_and_saveexec_b64 s[4:5], s[0:1]
	s_cbranch_execz .LBB0_573
	s_setprio 3
	s_ashr_i32 s41, s40, 31
	s_lshl_b64 s[6:7], s[40:41], 17
	s_add_u32 s6, s70, s6
	s_addc_u32 s7, s71, s7
	s_lshl_b32 s11, s10, 2
	s_add_u32 s6, s6, s11
	s_movk_i32 s11, 0x7f
	s_movk_i32 s25, 0x80
	v_and_b32_e32 v6, 0x7f, v196
	v_bitop3_b32 v7, v196, s11, v196 bitop3:0xc
	v_cmp_gt_u32_e32 vcc, s25, v196
	s_addc_u32 s7, s7, 0
	s_add_u32 s6, s6, 0xfc00000
	v_cndmask_b32_e32 v63, v7, v6, vcc
	v_ashrrev_i32_e32 v6, 4, v196
	v_and_or_b32 v6, v6, -8, s34
	v_or_b32_e32 v10, 4, v6
	v_ashrrev_i32_e32 v11, 31, v10
	s_addc_u32 s7, s7, 0
	v_lshlrev_b64 v[10:11], 13, v[10:11]
	v_lshlrev_b32_e32 v8, 2, v63
	v_mov_b32_e32 v9, 0
	v_lshl_add_u64 v[10:11], s[6:7], 0, v[10:11]
	v_lshl_add_u64 v[10:11], v[10:11], 0, v[8:9]
	v_ashrrev_i32_e32 v7, 31, v6
	v_lshlrev_b64 v[6:7], 13, v[6:7]
	v_lshl_add_u64 v[6:7], s[6:7], 0, v[6:7]
	v_lshl_add_u64 v[6:7], v[6:7], 0, v[8:9]
	s_waitcnt vmcnt(8)
	v_mov_b32_e32 v10, v72
	v_mov_b32_e32 v6, v73
	s_nop 1
	v_add_f32_dpp v10, v10, v10 row_shr:1 row_mask:0xf bank_mask:0xf
	s_nop 1
	v_add_f32_dpp v10, v10, v10 row_shr:2 row_mask:0xf bank_mask:0xf
	s_nop 1
	v_add_f32_dpp v10, v10, v10 row_shr:4 row_mask:0xf bank_mask:0xf
	s_nop 1
	v_add_f32_dpp v10, v10, v10 row_shr:8 row_mask:0xf bank_mask:0xf
	s_nop 1
	v_add_f32_dpp v10, v10, v10 row_bcast:15 row_mask:0xa bank_mask:0xf
	s_nop 1
	v_add_f32_dpp v10, v10, v10 row_bcast:31 row_mask:0xc bank_mask:0xf
	v_mov_b32_e32 v69, v10
	v_cmp_eq_u32_e32 vcc, 63, v197
	s_and_saveexec_b64 s[6:7], vcc
	v_lshl_add_u32 v7, v68, 2, 0
	v_add_u32_e32 v7, 0x21800, v7
	ds_write_b32 v7, v69
	s_or_b64 exec, exec, s[6:7]
.LBB0_573:
	s_setprio 0
	s_or_b64 exec, exec, s[4:5]
	s_or_b32 s4, s10, s53
	s_ashr_i32 s4, s4, 6
	s_and_b32 s4, s4, -4
	s_or_b32 s4, s4, s34
	v_ashrrev_i32_e32 v62, 8, v196
	v_add_u32_e32 v7, s50, v62
	s_ashr_i32 s5, s4, 31
	v_add_u32_e32 v44, 0x200, v196
	v_lshl_or_b32 v8, v7, 4, s24
	s_lshl_b64 s[4:5], s[4:5], 17
	v_readlane_b32 s6, v254, 35
	v_bfe_u32 v40, v196, 7, 2
	v_ashrrev_i32_e32 v45, 9, v44
	v_ashrrev_i32_e32 v9, 31, v8
	v_readlane_b32 s7, v254, 36
	s_add_u32 s4, s6, s4
	v_bfe_u32 v198, v196, 6, 1
	v_lshlrev_b32_e32 v199, 1, v40
	v_lshlrev_b32_e32 v12, 4, v45
	v_lshlrev_b64 v[8:9], 10, v[8:9]
	v_mov_b32_e32 v7, 2
	s_addc_u32 s5, s7, s5
	v_or3_b32 v12, v199, v12, v198
	v_lshl_add_u64 v[8:9], s[16:17], 0, v[8:9]
	v_lshlrev_b32_sdwa v60, v7, v196 dst_sel:DWORD dst_unused:UNUSED_PAD src0_sel:DWORD src1_sel:BYTE_0
	v_mov_b32_e32 v61, 0
	s_add_u32 s16, s4, 0x2000
	v_lshl_or_b32 v12, v12, 6, v197
	v_lshl_add_u64 v[8:9], v[8:9], 0, v[60:61]
	s_addc_u32 s17, s5, 0
	v_ashrrev_i32_e32 v13, 31, v12
	global_load_dword v7, v[8:9], off
	v_ashrrev_i32_e32 v41, 9, v196
	v_lshl_add_u64 v[12:13], v[12:13], 4, s[16:17]
	global_load_dwordx4 v[12:15], v[12:13], off nt
	v_lshlrev_b32_e32 v8, 4, v41
	v_or3_b32 v8, v199, v8, v198
	v_lshl_or_b32 v8, v8, 6, v197
	v_ashrrev_i32_e32 v9, 31, v8
	v_lshl_add_u64 v[8:9], v[8:9], 4, s[16:17]
	global_load_dwordx4 v[8:11], v[8:9], off nt
	v_add_u32_e32 v46, 0x400, v196
	v_ashrrev_i32_e32 v47, 9, v46
	v_lshlrev_b32_e32 v16, 4, v47
	v_or3_b32 v16, v199, v16, v198
	v_lshl_or_b32 v16, v16, 6, v197
	v_ashrrev_i32_e32 v17, 31, v16
	v_lshl_add_u64 v[16:17], v[16:17], 4, s[16:17]
	v_add_u32_e32 v48, 0x600, v196
	global_load_dwordx4 v[16:19], v[16:17], off nt
	v_ashrrev_i32_e32 v49, 9, v48
	v_lshlrev_b32_e32 v20, 4, v49
	v_or3_b32 v20, v199, v20, v198
	v_lshl_or_b32 v20, v20, 6, v197
	v_ashrrev_i32_e32 v21, 31, v20
	v_lshl_add_u64 v[20:21], v[20:21], 4, s[16:17]
	v_add_u32_e32 v50, 0x800, v196
	global_load_dwordx4 v[20:23], v[20:21], off nt
	v_ashrrev_i32_e32 v51, 9, v50
	v_lshlrev_b32_e32 v24, 4, v51
	v_or3_b32 v24, v199, v24, v198
	v_lshl_or_b32 v24, v24, 6, v197
	v_ashrrev_i32_e32 v25, 31, v24
	v_lshl_add_u64 v[24:25], v[24:25], 4, s[16:17]
	v_add_u32_e32 v52, 0xa00, v196
	global_load_dwordx4 v[24:27], v[24:25], off nt
; #define LAS __attribute__((address_space(3)))
; __device__ void passB_unit(const Params& p, LAS unsigned char* lds, int u, bool do_store = true) {
;     ...
;     { const int d = tid >> 8, k = tid & 255; nvec[tid] = ((const float*)(p.ws + OFF_NST))[(size_t)((sid0 + d) * 16 + c) * 256 + k]; }
; #pragma unroll
;     for (int i = 0; i < 8; ++i) { const int id = tid + 512 * i; const int w = id >> 9, m = (id >> 7) & 3, bj = (id >> 6) & 1, ln = id & 63;
;         *(LAS u32x4*)(Qs + ((w >> 2) * 64 + m * 16 + (ln & 15)) * 264 + bj * 128 + (w & 3) * 32 + (ln >> 4) * 8) = __builtin_nontemporal_load((const u32x4*)(Qg + (size_t)((w * 16 + m * 2 + bj) * 64 + ln) * 8)); }
;     __syncthreads();
;     float sc_a = 0.f, sc_pm = 0.f;
;     if (tid < 256) { if (wid & 1) sc_b += wtot[wid - 1];
;         sc_a = sc_li - sc_b; float pm = sc_a;
; #pragma unroll
;         for (int off = 1; off < 64; off <<= 1) { const float n = __shfl_up(pm, off); pm = (lane >= off) ? fmaxf(pm, n) : pm; }
;         sc_pm = pm; if (lane == 63) wmax[wid] = pm; }
;     __syncthreads();
;     const int wt2 = wid >> 2, w4 = wid & 3;
;     const bf16_t* Kg = (const bf16_t*)(p.ws + OFF_K) + (size_t)((b * 16 + c) * 4 + h) * 32768 + (size_t)(w4 * 2 * 8) * 512 + (fr * 4 + fq) * 8;
;     bf16x8 kfa[8][2];
; #pragma unroll
;     for (int ks = 0; ks < 8; ++ks)
; #pragma unroll
;         for (int nt = 0; nt < 2; ++nt) kfa[ks][nt] = *(const bf16x8*)(Kg + (size_t)(nt * 8 + ks) * 512);
	v_ashrrev_i32_e32 v53, 9, v52
	v_lshlrev_b32_e32 v28, 4, v53
	v_or3_b32 v28, v199, v28, v198
	v_lshl_or_b32 v28, v28, 6, v197
	v_ashrrev_i32_e32 v29, 31, v28
	v_lshl_add_u64 v[28:29], v[28:29], 4, s[16:17]
	v_add_u32_e32 v54, 0xc00, v196
	global_load_dwordx4 v[28:31], v[28:29], off nt
	v_ashrrev_i32_e32 v55, 9, v54
	v_lshlrev_b32_e32 v32, 4, v55
	v_or3_b32 v32, v199, v32, v198
	v_lshl_or_b32 v32, v32, 6, v197
	v_ashrrev_i32_e32 v33, 31, v32
	v_lshl_add_u64 v[32:33], v[32:33], 4, s[16:17]
	v_add_u32_e32 v56, 0xe00, v196
	global_load_dwordx4 v[32:35], v[32:33], off nt
	v_ashrrev_i32_e32 v57, 9, v56
	v_lshlrev_b32_e32 v36, 4, v57
	v_or3_b32 v36, v199, v36, v198
	v_lshl_or_b32 v36, v36, 6, v197
	v_ashrrev_i32_e32 v37, 31, v36
	v_lshl_add_u64 v[36:37], v[36:37], 4, s[16:17]
	global_load_dwordx4 v[36:39], v[36:37], off nt
	s_or_b32 s62, s24, s56
	s_lshl_b32 s62, s62, 2
	s_or_b32 s62, s62, s34
	s_ashr_i32 s63, s62, 31
	s_lshl_b64 s[62:63], s[62:63], 16
	s_add_u32 s62, s30, s62
	s_addc_u32 s63, s31, s63
	s_add_u32 s62, s62, 0x1000
	s_addc_u32 s63, s63, 0
	v_and_b32_e32 v160, 15, v196
	v_lshrrev_b32_e32 v161, 4, v197
	v_lshlrev_b32_e32 v160, 5, v160
	v_lshl_or_b32 v160, v161, 3, v160
	v_lshlrev_b32_e32 v160, 1, v160
	v_bfe_u32 v161, v196, 6, 2
	v_lshl_add_u32 v160, v161, 14, v160
	v_mov_b32_e32 v161, 0
	v_lshl_add_u64 v[162:163], s[62:63], 0, v[160:161]
	s_add_u32 s62, s62, 0x2000
	s_addc_u32 s63, s63, 0
	v_lshl_add_u64 v[164:165], s[62:63], 0, v[160:161]
	global_load_dwordx4 v[94:97], v[162:163], off offset:-4096
	global_load_dwordx4 v[98:101], v[162:163], off offset:-3072
	global_load_dwordx4 v[102:105], v[164:165], off offset:-4096
	global_load_dwordx4 v[106:109], v[164:165], off offset:-3072
	global_load_dwordx4 v[110:113], v[162:163], off offset:-2048
	global_load_dwordx4 v[114:117], v[162:163], off offset:-1024
	global_load_dwordx4 v[118:121], v[164:165], off offset:-2048
	global_load_dwordx4 v[122:125], v[164:165], off offset:-1024
	global_load_dwordx4 v[126:129], v[162:163], off
	global_load_dwordx4 v[130:133], v[162:163], off offset:1024
	global_load_dwordx4 v[134:137], v[164:165], off
	global_load_dwordx4 v[138:141], v[164:165], off offset:1024
	global_load_dwordx4 v[142:145], v[162:163], off offset:2048
	global_load_dwordx4 v[146:149], v[162:163], off offset:3072
	global_load_dwordx4 v[150:153], v[164:165], off offset:2048
	global_load_dwordx4 v[154:157], v[164:165], off offset:3072
	v_lshl_add_u32 v92, v196, 2, 0
	v_add_u32_e32 v42, 0x23400, v92
	v_and_b32_e32 v201, 15, v196
	v_lshlrev_b32_e32 v202, 4, v40
	v_lshlrev_b32_e32 v203, 8, v198
	v_add_u32_e32 v40, 0, v203
	s_movk_i32 s6, 0x210
	v_and_b32_e32 v60, 64, v196
	v_mov_b32_e32 v70, v61
	s_waitcnt vmcnt(24)
	ds_write_b32 v42, v7
	v_ashrrev_i32_e32 v42, 5, v196
	v_and_b32_e32 v42, 0xfffffc0, v42
	v_lshrrev_b32_e32 v7, 1, v196
	v_or3_b32 v42, v42, v202, v201
	v_and_b32_e32 v7, 24, v7
	v_mad_u64_u32 v[42:43], s[4:5], v42, s6, v[40:41]
	v_lshlrev_b32_e32 v41, 6, v41
	v_and_b32_e32 v41, 0xc0, v41
	v_lshlrev_b32_e32 v200, 1, v7
	v_add3_u32 v7, v42, v41, v200
	s_waitcnt vmcnt(22)
	ds_write_b128 v7, v[8:11]
	v_ashrrev_i32_e32 v7, 5, v44
	v_and_b32_e32 v7, 0xfffffc0, v7
	v_or3_b32 v7, v202, v7, v201
	v_mad_u64_u32 v[8:9], s[4:5], v7, s6, v[40:41]
	v_lshlrev_b32_e32 v7, 6, v45
	v_and_b32_e32 v7, 0xc0, v7
	v_add3_u32 v7, v8, v7, v200
	ds_write_b128 v7, v[12:15]
	v_ashrrev_i32_e32 v7, 5, v46
	v_and_b32_e32 v7, 0xfffffc0, v7
	v_or3_b32 v7, v202, v7, v201
	v_mad_u64_u32 v[8:9], s[4:5], v7, s6, v[40:41]
	v_lshlrev_b32_e32 v7, 6, v47
	v_and_b32_e32 v7, 0xc0, v7
	v_add3_u32 v7, v8, v7, v200
	s_waitcnt vmcnt(21)
	ds_write_b128 v7, v[16:19]
	v_ashrrev_i32_e32 v7, 5, v48
	v_and_b32_e32 v7, 0xfffffc0, v7
	v_or3_b32 v7, v202, v7, v201
	v_mad_u64_u32 v[8:9], s[4:5], v7, s6, v[40:41]
	v_lshlrev_b32_e32 v7, 6, v49
	v_and_b32_e32 v7, 0xc0, v7
	v_add3_u32 v7, v8, v7, v200
	s_waitcnt vmcnt(20)
	ds_write_b128 v7, v[20:23]
	v_ashrrev_i32_e32 v7, 5, v50
	v_and_b32_e32 v7, 0xfffffc0, v7
	v_or3_b32 v7, v202, v7, v201
	v_mad_u64_u32 v[8:9], s[4:5], v7, s6, v[40:41]
	v_lshlrev_b32_e32 v7, 6, v51
	v_and_b32_e32 v7, 0xc0, v7
	v_add3_u32 v7, v8, v7, v200
	s_waitcnt vmcnt(19)
	ds_write_b128 v7, v[24:27]
	v_ashrrev_i32_e32 v7, 5, v52
	v_and_b32_e32 v7, 0xfffffc0, v7
	v_or3_b32 v7, v202, v7, v201
	v_mad_u64_u32 v[8:9], s[4:5], v7, s6, v[40:41]
	v_lshlrev_b32_e32 v7, 6, v53
	v_and_b32_e32 v7, 0xc0, v7
	v_add3_u32 v7, v8, v7, v200
	s_waitcnt vmcnt(18)
	ds_write_b128 v7, v[28:31]
	v_ashrrev_i32_e32 v7, 5, v54
	v_and_b32_e32 v7, 0xfffffc0, v7
	v_or3_b32 v7, v202, v7, v201
	v_mad_u64_u32 v[8:9], s[4:5], v7, s6, v[40:41]
	v_lshlrev_b32_e32 v7, 6, v55
	v_and_b32_e32 v7, 0xc0, v7
	v_add3_u32 v7, v8, v7, v200
	s_waitcnt vmcnt(17)
	ds_write_b128 v7, v[32:35]
	v_ashrrev_i32_e32 v7, 5, v56
	v_and_b32_e32 v7, 0xfffffc0, v7
	v_or3_b32 v7, v202, v7, v201
	v_mad_u64_u32 v[8:9], s[4:5], v7, s6, v[40:41]
	v_lshlrev_b32_e32 v7, 6, v57
	v_and_b32_e32 v7, 0xc0, v7
	v_add3_u32 v7, v8, v7, v200
	s_waitcnt vmcnt(16)
	ds_write_b128 v7, v[36:39]
	s_waitcnt lgkmcnt(0)
	s_barrier
	s_and_saveexec_b64 s[6:7], s[0:1]
	s_cbranch_execz .LBB0_579
	s_setprio 3
	v_cmp_ne_u32_e32 vcc, 0, v60
	s_and_saveexec_b64 s[4:5], vcc
	s_cbranch_execz .LBB0_576
	v_lshlrev_b32_e32 v7, 2, v68
	s_add_i32 s10, 0, 0x21800
	v_add3_u32 v7, s10, v7, -4
	ds_read_b32 v7, v7
	s_waitcnt lgkmcnt(0)
	v_add_f32_e32 v69, v69, v7

; __device__ void passB_unit(const Params& p, LAS unsigned char* lds, int u, bool do_store = true) {
;     ...
;     if (tid < 256) { if (wid & 1) sc_b += wtot[wid - 1];
;         sc_a = sc_li - sc_b; float pm = sc_a;
; #pragma unroll
;         for (int off = 1; off < 64; off <<= 1) { const float n = __shfl_up(pm, off); pm = (lane >= off) ? fmaxf(pm, n) : pm; }
;         sc_pm = pm; if (lane == 63) wmax[wid] = pm; }
;     __syncthreads();
;     const int wt2 = wid >> 2, w4 = wid & 3;
;     const bf16_t* Kg = (const bf16_t*)(p.ws + OFF_K) + (size_t)((b * 16 + c) * 4 + h) * 32768 + (size_t)(w4 * 2 * 8) * 512 + (fr * 4 + fq) * 8;
;     bf16x8 kfa[8][2];
; #pragma unroll
;     for (int ks = 0; ks < 8; ++ks)
; #pragma unroll
;         for (int nt = 0; nt < 2; ++nt) kfa[ks][nt] = *(const bf16x8*)(Kg + (size_t)(nt * 8 + ks) * 512);
;     if (tid < 256) { const int d = tid >> 7, t = sc_t; if (wid & 1) sc_pm = fmaxf(sc_pm, wmax[wid - 1]);
.LBB0_579:
	s_setprio 0
	s_or_b64 exec, exec, s[6:7]
	s_or_b32 s40, s24, s56
	s_lshl_b32 s4, s40, 2
	s_or_b32 s4, s4, s34
	s_ashr_i32 s5, s4, 31
	s_lshl_b64 s[4:5], s[4:5], 16
	v_lshrrev_b32_e32 v93, 4, v197
	v_bfe_u32 v221, v196, 6, 2
	s_add_u32 s4, s30, s4
	v_lshlrev_b32_e32 v2, 5, v201
	s_addc_u32 s5, s31, s5
	v_lshlrev_b32_e32 v88, 14, v221
	v_mov_b32_e32 v89, 0
	v_lshl_or_b32 v2, v93, 3, v2
	v_lshl_add_u64 v[0:1], s[4:5], 0, v[88:89]
	v_lshlrev_b32_e32 v90, 1, v2
	v_mov_b32_e32 v91, v89
	v_lshl_add_u64 v[0:1], v[0:1], 0, v[90:91]
	s_movk_i32 s4, 0x2000
	v_add_co_u32_e32 v2, vcc, s4, v0
	s_movk_i32 s4, 0x1000
	s_nop 0
	v_addc_co_u32_e32 v3, vcc, 0, v1, vcc
	s_waitcnt lgkmcnt(0)
	s_barrier
	s_waitcnt vmcnt(0)
	v_mov_b32_e32 v52, v94
	v_mov_b32_e32 v53, v95
	v_mov_b32_e32 v54, v96
	v_mov_b32_e32 v55, v97
	v_mov_b32_e32 v44, v98
	v_mov_b32_e32 v45, v99
	v_mov_b32_e32 v46, v100
	v_mov_b32_e32 v47, v101
	v_mov_b32_e32 v56, v102
	v_mov_b32_e32 v57, v103
	v_mov_b32_e32 v58, v104
	v_mov_b32_e32 v59, v105
	v_mov_b32_e32 v48, v106
	v_mov_b32_e32 v49, v107
	v_mov_b32_e32 v50, v108
	v_mov_b32_e32 v51, v109
	v_mov_b32_e32 v36, v110
	v_mov_b32_e32 v37, v111
	v_mov_b32_e32 v38, v112
	v_mov_b32_e32 v39, v113
	v_mov_b32_e32 v28, v114
	v_mov_b32_e32 v29, v115
	v_mov_b32_e32 v30, v116
	v_mov_b32_e32 v31, v117
	v_mov_b32_e32 v40, v118
	v_mov_b32_e32 v41, v119
	v_mov_b32_e32 v42, v120
	v_mov_b32_e32 v43, v121
	v_mov_b32_e32 v32, v122
	v_mov_b32_e32 v33, v123
	v_mov_b32_e32 v34, v124
	v_mov_b32_e32 v35, v125
	v_mov_b32_e32 v20, v126
	v_mov_b32_e32 v21, v127
	v_mov_b32_e32 v22, v128
	v_mov_b32_e32 v23, v129
	v_mov_b32_e32 v12, v130
	v_mov_b32_e32 v13, v131
	v_mov_b32_e32 v14, v132
	v_mov_b32_e32 v15, v133
	v_mov_b32_e32 v24, v134
	v_mov_b32_e32 v25, v135
	v_mov_b32_e32 v26, v136
	v_mov_b32_e32 v27, v137
	v_mov_b32_e32 v16, v138
	v_mov_b32_e32 v17, v139
	v_mov_b32_e32 v18, v140
	v_mov_b32_e32 v19, v141
	v_mov_b32_e32 v8, v142
	v_mov_b32_e32 v9, v143
	v_mov_b32_e32 v10, v144
	v_mov_b32_e32 v11, v145
	v_mov_b32_e32 v0, v146
	v_mov_b32_e32 v1, v147
	v_mov_b32_e32 v2, v148
	v_mov_b32_e32 v3, v149
	v_mov_b32_e32 v4, v150
	v_mov_b32_e32 v5, v151
	v_mov_b32_e32 v6, v152
	v_mov_b32_e32 v7, v153
	v_mov_b32_e32 v64, v154
	v_mov_b32_e32 v65, v155
	v_mov_b32_e32 v66, v156
	v_mov_b32_e32 v67, v157
	s_and_saveexec_b64 s[4:5], s[0:1]
	s_cbranch_execz .LBB0_585
	s_setprio 3
	v_cmp_ne_u32_e32 vcc, 0, v60
	s_and_saveexec_b64 s[6:7], vcc
	s_cbranch_execz .LBB0_582
	v_lshlrev_b32_e32 v60, 2, v68
	s_add_i32 s10, 0, 0x21820
	v_add3_u32 v60, s10, v60, -4
	ds_read_b32 v60, v60
	v_max_f32_e32 v68, v70, v70
	s_waitcnt lgkmcnt(0)
	v_max_f32_e32 v60, v60, v60
	v_max_f32_e32 v70, v68, v60

; #define LAS __attribute__((address_space(3)))
; __device__ void passB_unit(const Params& p, LAS unsigned char* lds, int u, bool do_store = true) {
;     ...
;         for (int ks = 0; ks < 8; ++ks) { bf16x8 qf[4];
; #pragma unroll
;             for (int mt = 0; mt < 4; ++mt) qf[mt] = *(const LAS bf16x8*)(Qs + (wt2 * 64 + mt * 16 + fr) * 264 + ks * 32 + fq * 8);
; #pragma unroll
;             for (int mt = 0; mt < 4; ++mt)
; #pragma unroll
;                 for (int nt = 0; nt < 2; ++nt) sacc[mt][nt] = __builtin_amdgcn_mfma_f32_16x16x32_bf16(kfa[ks][nt], qf[mt], sacc[mt][nt], 0, 0, 0); }
.LBB0_585:
	s_setprio 0
	s_or_b64 exec, exec, s[4:5]
	v_lshl_or_b32 v209, v62, 6, v201
	s_movk_i32 s4, 0x210
	v_and_b32_e32 v124, 48, v196
	v_mul_lo_u32 v208, v209, s4
	v_add_u32_e32 v91, 0, v124
	v_add_u32_e32 v227, 0x2100, v208
	v_add_u32_e32 v223, 0x4200, v208
	v_add_u32_e32 v222, 0x6300, v208
	v_add_u32_e32 v215, v91, v208
	v_add_u32_e32 v114, v91, v227
	v_add_u32_e32 v115, v91, v223
	v_add_u32_e32 v91, v91, v222
	s_waitcnt lgkmcnt(0)
	s_barrier
	ds_read_b128 v[60:63], v215
	ds_read_b128 v[68:71], v215 offset:64
	ds_read_b128 v[76:79], v114
	ds_read_b128 v[80:83], v114 offset:64
	ds_read_b128 v[94:97], v115
	ds_read_b128 v[98:101], v115 offset:64
	ds_read_b128 v[106:109], v91
	ds_read_b128 v[110:113], v91 offset:64
	s_waitcnt vmcnt(15) lgkmcnt(7)
	v_mfma_f32_16x16x32_bf16 v[72:75], v[52:55], v[60:63], 0
	s_or_b32 s4, s59, s24
	s_lshl_b32 s4, s4, 17
	s_add_u32 s4, s58, s4
	s_waitcnt vmcnt(13)
	v_mfma_f32_16x16x32_bf16 v[60:63], v[56:59], v[60:63], 0
	s_addc_u32 s5, s57, 0
	v_lshlrev_b32_e32 v89, 13, v221
	s_waitcnt lgkmcnt(5)
	v_mfma_f32_16x16x32_bf16 v[84:87], v[52:55], v[76:79], 0
	v_mfma_f32_16x16x32_bf16 v[76:79], v[56:59], v[76:79], 0
	s_waitcnt lgkmcnt(3)
	v_mfma_f32_16x16x32_bf16 v[102:105], v[52:55], v[94:97], 0
	v_mfma_f32_16x16x32_bf16 v[94:97], v[56:59], v[94:97], 0
	s_waitcnt lgkmcnt(1)
	v_mfma_f32_16x16x32_bf16 v[52:55], v[52:55], v[106:109], 0
	v_mfma_f32_16x16x32_bf16 v[56:59], v[56:59], v[106:109], 0
	v_mfma_f32_16x16x32_bf16 v[72:75], v[44:47], v[68:71], v[72:75]
	s_waitcnt vmcnt(12)
	v_mfma_f32_16x16x32_bf16 v[60:63], v[48:51], v[68:71], v[60:63]
	v_mfma_f32_16x16x32_bf16 v[68:71], v[44:47], v[80:83], v[84:87]
	v_mfma_f32_16x16x32_bf16 v[76:79], v[48:51], v[80:83], v[76:79]
	v_mfma_f32_16x16x32_bf16 v[80:83], v[44:47], v[98:101], v[102:105]
	v_mfma_f32_16x16x32_bf16 v[84:87], v[48:51], v[98:101], v[94:97]
	s_waitcnt lgkmcnt(0)
	v_mfma_f32_16x16x32_bf16 v[44:47], v[44:47], v[110:113], v[52:55]
	v_mfma_f32_16x16x32_bf16 v[48:51], v[48:51], v[110:113], v[56:59]
	s_nop 1
	ds_read_b128 v[52:55], v215 offset:128
	ds_read_b128 v[56:59], v215 offset:192
	s_waitcnt vmcnt(11) lgkmcnt(1)
	v_mfma_f32_16x16x32_bf16 v[72:75], v[36:39], v[52:55], v[72:75]
	s_waitcnt vmcnt(9)
	v_mfma_f32_16x16x32_bf16 v[52:55], v[40:43], v[52:55], v[60:63]
	s_nop 2
	ds_read_b128 v[60:63], v114 offset:128
	ds_read_b128 v[94:97], v114 offset:192
	s_waitcnt lgkmcnt(1)
	v_mfma_f32_16x16x32_bf16 v[68:71], v[36:39], v[60:63], v[68:71]
	v_mfma_f32_16x16x32_bf16 v[60:63], v[40:43], v[60:63], v[76:79]
	s_nop 2
	ds_read_b128 v[76:79], v115 offset:128
	ds_read_b128 v[98:101], v115 offset:192
	s_waitcnt lgkmcnt(1)
	v_mfma_f32_16x16x32_bf16 v[80:83], v[36:39], v[76:79], v[80:83]
	v_mfma_f32_16x16x32_bf16 v[76:79], v[40:43], v[76:79], v[84:87]
	s_nop 2
	ds_read_b128 v[84:87], v91 offset:128
	ds_read_b128 v[102:105], v91 offset:192
	s_waitcnt lgkmcnt(1)
	v_mfma_f32_16x16x32_bf16 v[36:39], v[36:39], v[84:87], v[44:47]
	v_mfma_f32_16x16x32_bf16 v[40:43], v[40:43], v[84:87], v[48:51]
	v_mfma_f32_16x16x32_bf16 v[44:47], v[28:31], v[56:59], v[72:75]
	s_waitcnt vmcnt(8)
	v_mfma_f32_16x16x32_bf16 v[48:51], v[32:35], v[56:59], v[52:55]
	v_mfma_f32_16x16x32_bf16 v[52:55], v[28:31], v[94:97], v[68:71]
	v_mfma_f32_16x16x32_bf16 v[56:59], v[32:35], v[94:97], v[60:63]
	v_mfma_f32_16x16x32_bf16 v[60:63], v[28:31], v[98:101], v[80:83]
	v_mfma_f32_16x16x32_bf16 v[68:71], v[32:35], v[98:101], v[76:79]
	s_waitcnt lgkmcnt(0)
	v_mfma_f32_16x16x32_bf16 v[28:31], v[28:31], v[102:105], v[36:39]
	v_mfma_f32_16x16x32_bf16 v[32:35], v[32:35], v[102:105], v[40:43]
	s_nop 1
	ds_read_b128 v[36:39], v215 offset:256
	ds_read_b128 v[40:43], v215 offset:320
	s_waitcnt vmcnt(7) lgkmcnt(1)
	v_mfma_f32_16x16x32_bf16 v[44:47], v[20:23], v[36:39], v[44:47]
	s_waitcnt vmcnt(5)
	v_mfma_f32_16x16x32_bf16 v[36:39], v[24:27], v[36:39], v[48:51]
	s_nop 2
	ds_read_b128 v[48:51], v114 offset:256
	ds_read_b128 v[72:75], v114 offset:320
	s_waitcnt lgkmcnt(1)
	v_mfma_f32_16x16x32_bf16 v[52:55], v[20:23], v[48:51], v[52:55]
	v_mfma_f32_16x16x32_bf16 v[48:51], v[24:27], v[48:51], v[56:59]
	s_nop 2
	ds_read_b128 v[56:59], v115 offset:256
	ds_read_b128 v[76:79], v115 offset:320
	s_waitcnt lgkmcnt(1)
	v_mfma_f32_16x16x32_bf16 v[60:63], v[20:23], v[56:59], v[60:63]
	v_mfma_f32_16x16x32_bf16 v[56:59], v[24:27], v[56:59], v[68:71]
	s_nop 2
	ds_read_b128 v[68:71], v91 offset:256
	ds_read_b128 v[80:83], v91 offset:320
	s_waitcnt lgkmcnt(1)
	v_mfma_f32_16x16x32_bf16 v[20:23], v[20:23], v[68:71], v[28:31]
	v_mfma_f32_16x16x32_bf16 v[24:27], v[24:27], v[68:71], v[32:35]
	v_mfma_f32_16x16x32_bf16 v[28:31], v[12:15], v[40:43], v[44:47]
	s_waitcnt vmcnt(4)
	v_mfma_f32_16x16x32_bf16 v[32:35], v[16:19], v[40:43], v[36:39]
	v_mfma_f32_16x16x32_bf16 v[36:39], v[12:15], v[72:75], v[52:55]
	v_mfma_f32_16x16x32_bf16 v[40:43], v[16:19], v[72:75], v[48:51]
	v_mfma_f32_16x16x32_bf16 v[44:47], v[12:15], v[76:79], v[60:63]
	v_mfma_f32_16x16x32_bf16 v[48:51], v[16:19], v[76:79], v[56:59]
	s_waitcnt lgkmcnt(0)
	v_mfma_f32_16x16x32_bf16 v[12:15], v[12:15], v[80:83], v[20:23]
	v_mfma_f32_16x16x32_bf16 v[16:19], v[16:19], v[80:83], v[24:27]
	s_nop 1
	ds_read_b128 v[20:23], v215 offset:384
	ds_read_b128 v[24:27], v215 offset:448
	s_waitcnt vmcnt(3) lgkmcnt(1)
	v_mfma_f32_16x16x32_bf16 v[28:31], v[8:11], v[20:23], v[28:31]
	s_waitcnt vmcnt(1)
	v_mfma_f32_16x16x32_bf16 v[20:23], v[4:7], v[20:23], v[32:35]
	s_nop 2
	ds_read_b128 v[32:35], v114 offset:384
	ds_read_b128 v[60:63], v114 offset:448
	s_waitcnt lgkmcnt(1)
; #define LAS __attribute__((address_space(3)))
; __device__ __forceinline__ unsigned cvt_pk_bf16(float lo, float hi) { unsigned r; asm volatile("v_cvt_pk_bf16_f32 %0, %1, %2" : "=v"(r) : "v"(lo), "v"(hi)); return r; }
; __device__ void passB_unit(const Params& p, LAS unsigned char* lds, int u, bool do_store = true) {
;     ...
;         for (int ks = 0; ks < 8; ++ks) { bf16x8 qf[4];
; #pragma unroll
;             for (int mt = 0; mt < 4; ++mt) qf[mt] = *(const LAS bf16x8*)(Qs + (wt2 * 64 + mt * 16 + fr) * 264 + ks * 32 + fq * 8);
; #pragma unroll
;             for (int mt = 0; mt < 4; ++mt)
; #pragma unroll
;                 for (int nt = 0; nt < 2; ++nt) sacc[mt][nt] = __builtin_amdgcn_mfma_f32_16x16x32_bf16(kfa[ks][nt], qf[mt], sacc[mt][nt], 0, 0, 0); }
;         PB_ISSUE(0); PB_ISSUE(1);
;         __builtin_amdgcn_sched_barrier(0);
; #pragma unroll
;         for (int mt = 0; mt < 4; ++mt) { const int t = wt2 * 64 + mt * 16 + fr; const float Mf = MA[t], Mb = MA[128 + t]; float rf = 0.f, rb = 0.f;
; #pragma unroll
;             for (int nt = 0; nt < 2; ++nt) { const int s0 = w4 * 32 + nt * 16 + fq * 4; float pf[4], pb[4];
; #pragma unroll
;                 for (int r = 0; r < 4; ++r) { const int s = s0 + r; const float val = sacc[mt][nt][r];
;                     const float ef = __expf(fminf(aA[s] - Mf, 0.f)), eb = __expf(fminf(aA[128 + s] - Mb, 0.f));
;                     pf[r] = (s <= t) ? val * ef : 0.f; pb[r] = (s >= t) ? val * eb : 0.f; rf += pf[r]; rb += pb[r]; }
;                 u32x2 wf, wb; wf.x = cvt_pk_bf16(pf[0], pf[1]); wf.y = cvt_pk_bf16(pf[2], pf[3]); wb.x = cvt_pk_bf16(pb[0], pb[1]); wb.y = cvt_pk_bf16(pb[2], pb[3]);
;                 *(LAS u32x2*)(Pd + t * 136 + s0) = wf; *(LAS u32x2*)(Pd + 128 * 136 + t * 136 + s0) = wb; }
	v_mfma_f32_16x16x32_bf16 v[36:39], v[8:11], v[32:35], v[36:39]
	v_mfma_f32_16x16x32_bf16 v[32:35], v[4:7], v[32:35], v[40:43]
	s_nop 2
	ds_read_b128 v[40:43], v115 offset:384
	ds_read_b128 v[68:71], v115 offset:448
	ds_read_b128 v[98:101], v91 offset:448
	s_waitcnt lgkmcnt(2)
	v_mfma_f32_16x16x32_bf16 v[72:75], v[8:11], v[40:43], v[44:47]
	s_nop 2
	ds_read_b128 v[44:47], v91 offset:384
	s_waitcnt lgkmcnt(0)
	v_mfma_f32_16x16x32_bf16 v[12:15], v[8:11], v[44:47], v[12:15]
	v_mov_b32_e32 v9, 0
	v_lshlrev_b32_e32 v8, 15, v221
	v_lshl_add_u64 v[10:11], s[4:5], 0, v[8:9]
	v_mov_b32_e32 v91, v9
	v_lshl_add_u64 v[136:137], v[10:11], 0, v[90:91]
	s_movk_i32 s4, 0x2000
	v_mfma_f32_16x16x32_bf16 v[94:97], v[4:7], v[40:43], v[48:51]
	v_mfma_f32_16x16x32_bf16 v[102:105], v[4:7], v[44:47], v[16:19]
	v_add_co_u32_e32 v4, vcc, s4, v136
	s_movk_i32 s4, 0x3000
	s_nop 0
	v_addc_co_u32_e32 v5, vcc, 0, v137, vcc
	v_add_co_u32_e32 v114, vcc, s4, v136
	s_movk_i32 s4, 0x1000
	s_nop 0
	v_addc_co_u32_e32 v115, vcc, 0, v137, vcc
	v_add_co_u32_e32 v6, vcc, s4, v136
	v_mfma_f32_16x16x32_bf16 v[106:109], v[0:3], v[24:27], v[28:31]
	s_nop 0
	v_addc_co_u32_e32 v7, vcc, 0, v137, vcc
	global_load_dwordx4 v[56:59], v[136:137], off nt
	global_load_dwordx4 v[48:51], v[136:137], off offset:1024 nt
	global_load_dwordx4 v[52:55], v[4:5], off offset:1024 nt
	global_load_dwordx4 v[40:43], v[4:5], off offset:2048 nt
	s_waitcnt vmcnt(4)
	v_mfma_f32_16x16x32_bf16 v[110:113], v[64:67], v[24:27], v[20:23]
	v_mfma_f32_16x16x32_bf16 v[84:87], v[0:3], v[60:63], v[36:39]
	v_mfma_f32_16x16x32_bf16 v[80:83], v[64:67], v[60:63], v[32:35]
	global_load_dwordx4 v[44:47], v[136:137], off offset:2048 nt
	s_nop 1
	global_load_dwordx4 v[32:35], v[136:137], off offset:3072 nt
	global_load_dwordx4 v[36:39], v[4:5], off offset:3072 nt
	global_load_dwordx4 v[24:27], v[6:7], off nt
	global_load_dwordx4 v[28:31], v[114:115], off nt
	global_load_dwordx4 v[16:19], v[114:115], off offset:1024 nt
	global_load_dwordx4 v[20:23], v[6:7], off offset:1024 nt
	global_load_dwordx4 v[8:11], v[6:7], off offset:2048 nt
	v_mfma_f32_16x16x32_bf16 v[76:79], v[0:3], v[68:71], v[72:75]
	v_mfma_f32_16x16x32_bf16 v[72:75], v[64:67], v[68:71], v[94:97]
	v_mfma_f32_16x16x32_bf16 v[68:71], v[0:3], v[98:101], v[12:15]
	global_load_dwordx4 v[60:63], v[114:115], off offset:-4096 nt
	s_nop 0
	global_load_dwordx4 v[4:7], v[6:7], off offset:3072 nt
	s_nop 0
	global_load_dwordx4 v[12:15], v[114:115], off offset:2048 nt
	global_load_dwordx4 v[0:3], v[114:115], off offset:3072 nt
	v_mfma_f32_16x16x32_bf16 v[64:67], v[64:67], v[98:101], v[102:105]
	v_lshlrev_b32_e32 v210, 2, v93
	v_lshl_or_b32 v91, v221, 5, v210
	v_lshl_add_u32 v93, v209, 2, 0
	v_add_u32_e32 v93, 0x22400, v93
	v_lshl_add_u32 v96, v91, 2, s51
	ds_read2st64_b32 v[118:119], v93 offset1:2
	ds_read_b128 v[100:103], v96
	ds_read_b128 v[114:117], v96 offset:512
	s_movk_i32 s6, 0x88
	v_cmp_gt_i32_e32 vcc, v91, v209
	v_mul_lo_u32 v104, v209, s6
	s_waitcnt lgkmcnt(1)
	v_sub_f32_e32 v94, v100, v118
	v_min_f32_e32 v94, 0, v94
	s_waitcnt lgkmcnt(0)
	v_sub_f32_e32 v95, v114, v119
	v_mul_f32_e32 v94, 0x3fb8aa3b, v94
	v_min_f32_e32 v95, 0, v95
	v_sub_f32_e32 v99, v115, v119
	v_exp_f32_e32 v94, v94
	v_mul_f32_e32 v95, 0x3fb8aa3b, v95
	v_min_f32_e32 v99, 0, v99
	v_exp_f32_e32 v95, v95
	v_mul_f32_e32 v99, 0x3fb8aa3b, v99
	v_exp_f32_e32 v99, v99
	v_mul_f32_e32 v94, v106, v94
	v_cndmask_b32_e64 v97, v94, 0, vcc
	v_mul_f32_e32 v94, v106, v95
	v_cmp_lt_i32_e64 s[6:7], v91, v209
	v_sub_f32_e32 v98, v101, v118
	v_or_b32_e32 v100, 1, v91
	v_cndmask_b32_e64 v105, v94, 0, s[6:7]
	v_min_f32_e32 v98, 0, v98
	v_mul_f32_e32 v99, v107, v99
	v_cmp_ge_i32_e64 s[10:11], v100, v209
	v_add_f32_e32 v95, 0, v105
	v_mul_f32_e32 v98, 0x3fb8aa3b, v98
	v_cndmask_b32_e64 v101, 0, v99, s[10:11]
	v_exp_f32_e32 v98, v98
	v_add_f32_e32 v114, v95, v101
	v_sub_f32_e32 v95, v102, v118
	v_min_f32_e32 v95, 0, v95
	v_mul_f32_e32 v95, 0x3fb8aa3b, v95
	v_exp_f32_e32 v95, v95
	v_mul_f32_e32 v98, v107, v98
	v_add_f32_e32 v94, 0, v97
	v_cndmask_b32_e64 v98, 0, v98, s[6:7]
	v_add_f32_e32 v99, v94, v98
	v_or_b32_e32 v94, 2, v91
	v_sub_f32_e32 v102, v116, v119
	v_mul_f32_e32 v95, v108, v95
	v_cmp_le_i32_e64 s[10:11], v94, v209
	v_min_f32_e32 v102, 0, v102
	v_mul_f32_e32 v102, 0x3fb8aa3b, v102
	v_cndmask_b32_e64 v106, 0, v95, s[10:11]
	v_add_f32_e32 v115, v99, v106
	v_sub_f32_e32 v99, v103, v118
	v_exp_f32_e32 v102, v102
	v_min_f32_e32 v99, 0, v99
	v_sub_f32_e32 v103, v117, v119
	v_mul_f32_e32 v99, 0x3fb8aa3b, v99
	v_min_f32_e32 v103, 0, v103
	v_exp_f32_e32 v99, v99
	v_mul_f32_e32 v103, 0x3fb8aa3b, v103
	v_exp_f32_e32 v103, v103
	v_mul_f32_e32 v95, v108, v102
	v_cmp_ge_i32_e64 s[10:11], v94, v209
	v_mul_f32_e32 v99, v109, v99
	v_lshlrev_b32_e32 v93, 1, v104
	v_cndmask_b32_e64 v102, 0, v95, s[10:11]
	v_or_b32_e32 v95, 3, v91
	v_cmp_le_i32_e64 s[10:11], v95, v209
	v_cvt_pk_bf16_f32 v98, v97, v98
	v_add_f32_e32 v97, v114, v102
	v_lshlrev_b32_e32 v214, 9, v221
	v_cndmask_b32_e64 v116, 0, v99, s[10:11]
	v_mul_f32_e32 v99, v109, v103
	v_lshlrev_b32_e32 v103, 1, v91
	v_cmp_ge_i32_e64 s[10:11], v95, v209
	v_add3_u32 v121, s46, v93, v103
	v_add3_u32 v122, s48, v93, v103
	v_or_b32_e32 v93, 16, v91
	v_cndmask_b32_e64 v117, 0, v99, s[10:11]
	v_cvt_pk_bf16_f32 v99, v106, v116
	v_cvt_pk_bf16_f32 v106, v105, v101
	v_cvt_pk_bf16_f32 v107, v102, v117
	ds_write_b64 v121, v[98:99]
	ds_write_b64 v122, v[106:107]
	v_lshl_add_u32 v101, v93, 2, s51
	ds_read_b128 v[106:109], v101
	v_add_f32_e32 v98, v115, v116
	v_add_f32_e32 v97, v97, v117
	ds_read_b128 v[114:117], v101 offset:512
	v_cmp_le_i32_e64 s[10:11], v93, v209
	s_waitcnt lgkmcnt(1)
; #define LAS __attribute__((address_space(3)))
; __device__ __forceinline__ unsigned cvt_pk_bf16(float lo, float hi) { unsigned r; asm volatile("v_cvt_pk_bf16_f32 %0, %1, %2" : "=v"(r) : "v"(lo), "v"(hi)); return r; }
; __device__ void passB_unit(const Params& p, LAS unsigned char* lds, int u, bool do_store = true) {
;     ...
;         for (int mt = 0; mt < 4; ++mt) { const int t = wt2 * 64 + mt * 16 + fr; const float Mf = MA[t], Mb = MA[128 + t]; float rf = 0.f, rb = 0.f;
; #pragma unroll
;             for (int nt = 0; nt < 2; ++nt) { const int s0 = w4 * 32 + nt * 16 + fq * 4; float pf[4], pb[4];
; #pragma unroll
;                 for (int r = 0; r < 4; ++r) { const int s = s0 + r; const float val = sacc[mt][nt][r];
;                     const float ef = __expf(fminf(aA[s] - Mf, 0.f)), eb = __expf(fminf(aA[128 + s] - Mb, 0.f));
;                     pf[r] = (s <= t) ? val * ef : 0.f; pb[r] = (s >= t) ? val * eb : 0.f; rf += pf[r]; rb += pb[r]; }
;                 u32x2 wf, wb; wf.x = cvt_pk_bf16(pf[0], pf[1]); wf.y = cvt_pk_bf16(pf[2], pf[3]); wb.x = cvt_pk_bf16(pb[0], pb[1]); wb.y = cvt_pk_bf16(pb[2], pb[3]);
;                 *(LAS u32x2*)(Pd + t * 136 + s0) = wf; *(LAS u32x2*)(Pd + 128 * 136 + t * 136 + s0) = wb; }
;             rf += __shfl_xor(rf, 16); rf += __shfl_xor(rf, 32); rb += __shfl_xor(rb, 16); rb += __shfl_xor(rb, 32);
;             if (fq == 0) { rsP[w4 * 128 + t] = rf; rsP[512 + w4 * 128 + t] = rb; } }
	v_sub_f32_e32 v99, v106, v118
	v_sub_f32_e32 v106, v107, v118
	v_min_f32_e32 v106, 0, v106
	s_waitcnt lgkmcnt(0)
	v_sub_f32_e32 v107, v115, v119
	v_min_f32_e32 v107, 0, v107
	v_mul_f32_e32 v106, 0x3fb8aa3b, v106
	v_mul_f32_e32 v107, 0x3fb8aa3b, v107
	v_min_f32_e32 v99, 0, v99
	v_sub_f32_e32 v102, v114, v119
	v_exp_f32_e32 v106, v106
	v_exp_f32_e32 v107, v107
	v_mul_f32_e32 v99, 0x3fb8aa3b, v99
	v_min_f32_e32 v102, 0, v102
	v_exp_f32_e32 v99, v99
	v_mul_f32_e32 v102, 0x3fb8aa3b, v102
	v_exp_f32_e32 v102, v102
	v_mul_f32_e32 v106, v111, v106
	v_mul_f32_e32 v107, v111, v107
	v_sub_f32_e32 v108, v108, v118
	v_sub_f32_e32 v111, v116, v119
	v_min_f32_e32 v108, 0, v108
	v_min_f32_e32 v111, 0, v111
	v_mul_f32_e32 v99, v110, v99
	v_mul_f32_e32 v108, 0x3fb8aa3b, v108
	v_mul_f32_e32 v111, 0x3fb8aa3b, v111
	v_cndmask_b32_e64 v105, 0, v99, s[10:11]
	v_mul_f32_e32 v99, v110, v102
	v_cmp_ge_i32_e64 s[10:11], v93, v209
	v_exp_f32_e32 v108, v108
	v_exp_f32_e32 v111, v111
	v_cndmask_b32_e64 v102, 0, v99, s[10:11]
	v_add_f32_e32 v99, v97, v102
	v_or_b32_e32 v97, 17, v91
	v_cmp_le_i32_e64 s[10:11], v97, v209
	v_sub_f32_e32 v109, v109, v118
	v_add_f32_e32 v98, v98, v105
	v_cndmask_b32_e64 v106, 0, v106, s[10:11]
	v_mul_f32_e32 v108, v112, v108
	v_mul_f32_e32 v111, v112, v111
	v_min_f32_e32 v109, 0, v109
	v_sub_f32_e32 v112, v117, v119
	v_cmp_ge_i32_e64 s[10:11], v97, v209
	v_add_f32_e32 v110, v98, v106
	v_or_b32_e32 v98, 18, v91
	v_mul_f32_e32 v109, 0x3fb8aa3b, v109
	v_min_f32_e32 v112, 0, v112
	v_cndmask_b32_e64 v107, 0, v107, s[10:11]
	v_cmp_le_i32_e64 s[10:11], v98, v209
	v_exp_f32_e32 v109, v109
	v_mul_f32_e32 v112, 0x3fb8aa3b, v112
	v_cndmask_b32_e64 v108, 0, v108, s[10:11]
	v_cmp_ge_i32_e64 s[10:11], v98, v209
	v_exp_f32_e32 v112, v112
	v_add_f32_e32 v99, v99, v107
	v_cndmask_b32_e64 v114, 0, v111, s[10:11]
	v_add_f32_e32 v111, v99, v114
	v_or_b32_e32 v99, 19, v91
	v_mul_f32_e32 v109, v113, v109
	v_cmp_le_i32_e64 s[10:11], v99, v209
	v_mul_f32_e32 v112, v113, v112
	v_add_f32_e32 v110, v110, v108
	v_cndmask_b32_e64 v109, 0, v109, s[10:11]
	v_cmp_ge_i32_e64 s[10:11], v99, v209
	v_add_f32_e32 v115, v110, v109
	v_cndmask_b32_e64 v113, 0, v112, s[10:11]
	v_add_f32_e32 v116, v111, v113
	v_cvt_pk_bf16_f32 v110, v105, v106
	v_cvt_pk_bf16_f32 v111, v108, v109
	v_cvt_pk_bf16_f32 v112, v102, v107
	s_waitcnt lgkmcnt(0)
	v_mov_b32_e32 v117, v115
	v_mov_b32_e32 v105, v115
	s_nop 1
	v_permlane16_swap_b32_e32 v117, v105
	v_add_f32_e32 v105, v105, v117
	s_waitcnt lgkmcnt(0)
	v_mov_b32_e32 v118, v116
	v_mov_b32_e32 v107, v116
	s_nop 1
	v_permlane16_swap_b32_e32 v118, v107
	v_add_f32_e32 v107, v107, v118
	v_mov_b32_e32 v106, v105
	s_nop 1
	v_permlane32_swap_b32_e32 v106, v105
	v_mov_b32_e32 v108, v107
	s_nop 1
	v_permlane32_swap_b32_e32 v108, v107
	v_add_u32_e32 v120, s47, v214
	v_cmp_gt_u32_e64 s[4:5], 16, v197
	v_lshl_add_u32 v102, v209, 2, v120
	v_cvt_pk_bf16_f32 v113, v114, v113
	ds_write_b64 v121, v[110:111] offset:32
	ds_write_b64 v122, v[112:113] offset:32
	s_and_saveexec_b64 s[10:11], s[4:5]
	s_cbranch_execz .LBB0_587
	s_waitcnt lgkmcnt(2)
	v_add_f32_e32 v107, v107, v108
	v_add_f32_e32 v105, v105, v106
	ds_write2st64_b32 v102, v105, v107 offset1:8
